# phase2+phase7 GEMM loops: prefetch loads hoisted, LDS stores interleaved with MFMAs; phase2 hand-written store epilogue; scan inner loop unrolled x8
# speedup vs baseline: 1.0240x; 1.0100x over previous
; template <int CTRL> DI float dppf(float v) { return __int_as_float(__builtin_amdgcn_update_dpp(0, __float_as_int(v), CTRL, 0xf, 0xf, false)); }
; DI float red16(float p) { p += dppf<0xB1>(p); p += dppf<0x4E>(p); p += dppf<0x141>(p); p += dppf<0x140>(p); return p; }
; DI void scan_task(const Params& P, int sb, unsigned char* lds) {
;     ...
;       for (int g4 = 0; g4 < CH / 4; ++g4) {
;         const float* gb = cb + g4 * 4 * SREC;
;         const float4 v4 = *(const float4*)(vrow + g4 * 4);
;         float pp[4];
; #pragma unroll
;         for (int i = 0; i < 4; ++i) {
;           ld_ops(nx3, gb + (i + 3) * SREC, q4);
;           const f2 a01 = {cur.a.x, cur.a.y}, a23 = {cur.a.z, cur.a.w}, w01 = {cur.w.x, cur.w.y}, w23 = {cur.w.z, cur.w.w};
;           const f2 k01 = {cur.k.x, cur.k.y}, k23 = {cur.k.z, cur.k.w}, b01 = {cur.b.x, cur.b.y}, b23 = {cur.b.z, cur.b.w};
;           const f2 r01 = {cur.r.x, cur.r.y}, r23 = {cur.r.z, cur.r.w};
;           f2 pa = S0 * a01; pa += S1 * a23;
;           const float vs = (i == 0) ? v4.x : (i == 1) ? v4.y : (i == 2) ? v4.z : v4.w;
;           const f2 vv = {vs, vs};
;           const f2 t0 = S0 * w01 + vv * k01, t1 = S1 * w23 + vv * k23;
;           const float sa = red16(pa.x + pa.y);
;           const f2 sa2 = {sa, sa};
;           S0 = t0 + sa2 * b01; S1 = t1 + sa2 * b23;
;           f2 py = S0 * r01; py += S1 * r23;
;           pp[i] = py.x + py.y;
;           cur = nxt; nxt = nx2; nx2 = nx3;
;         }
;         const float tA = o1 ? pp[0] : pp[1], kA = o1 ? pp[1] : pp[0];
;         const float tB = o1 ? pp[2] : pp[3], kB = o1 ? pp[3] : pp[2];
;         const float r0 = kA + dppf<0xB1>(tA), r1 = kB + dppf<0xB1>(tB);
;         const float tC = o2 ? r0 : r1, kC = o2 ? r1 : r0;
;         float u = kC + dppf<0x4E>(tC);
;         u += dppf<0x124>(u);
;         u += dppf<0x128>(u);
;         yb[(g4 * 4 + (q & 3)) * 16 + rowl] = u;
.LBB0_1198:
	v_add_u32_e32 v100, 0x18000, v74
	s_waitcnt lgkmcnt(14)
	v_pk_mul_f32 v[2:3], v[64:65], v[2:3]
	ds_read_b128 v[60:63], v72 offset:256
	ds_read_b128 v[76:79], v72 offset:512
	ds_read_b128 v[80:83], v72 offset:768
	ds_read_b128 v[84:87], v72 offset:1024
	ds_read_b128 v[88:91], v100
	ds_read_b128 v[92:95], v72
	v_pk_fma_f32 v[96:97], v[66:67], v[0:1], v[2:3]
	ds_read_b128 v[0:3], v72 offset:1408
	v_add_f32_e32 v75, v96, v97
	s_waitcnt lgkmcnt(2)
	v_pk_mul_f32 v[14:15], v[14:15], v[88:89] op_sel_hi:[1,0]
	v_pk_mul_f32 v[12:13], v[12:13], v[88:89] op_sel_hi:[1,0]
	v_add_f32_dpp v75, v75, v75 quad_perm:[1,0,3,2] row_mask:0xf bank_mask:0xf bound_ctrl:1
	v_pk_fma_f32 v[64:65], v[64:65], v[10:11], v[14:15]
	v_pk_fma_f32 v[66:67], v[66:67], v[8:9], v[12:13]
	v_add_f32_dpp v75, v75, v75 quad_perm:[2,3,0,1] row_mask:0xf bank_mask:0xf bound_ctrl:1
	v_mov_b32_e32 v98, v91
	ds_read_b128 v[8:11], v72 offset:1920
	ds_read_b128 v[12:15], v72 offset:2176
	v_add_f32_dpp v75, v75, v75 row_half_mirror row_mask:0xf bank_mask:0xf bound_ctrl:1
	s_nop 1
	v_add_f32_dpp v96, v75, v75 row_mirror row_mask:0xf bank_mask:0xf bound_ctrl:1
	v_pk_fma_f32 v[64:65], v[6:7], v[96:97], v[64:65] op_sel_hi:[1,0,1]
	v_pk_fma_f32 v[66:67], v[4:5], v[96:97], v[66:67] op_sel_hi:[1,0,1]
	v_pk_mul_f32 v[18:19], v[18:19], v[64:65]
	v_pk_mul_f32 v[22:23], v[22:23], v[64:65]
	v_pk_mul_f32 v[36:37], v[36:37], v[66:67]
	v_pk_mul_f32 v[38:39], v[38:39], v[64:65]
	v_pk_fma_f32 v[64:65], v[16:17], v[66:67], v[18:19]
	v_pk_fma_f32 v[66:67], v[20:21], v[66:67], v[22:23]
	v_add_f32_e32 v75, v64, v65
	v_add_f32_e32 v64, v66, v67
	v_pk_fma_f32 v[36:37], v[28:29], v[88:89], v[36:37] op_sel:[0,1,0]
	v_pk_fma_f32 v[38:39], v[30:31], v[88:89], v[38:39] op_sel:[0,1,0]
	v_add_f32_dpp v64, v64, v64 quad_perm:[1,0,3,2] row_mask:0xf bank_mask:0xf bound_ctrl:1
	ds_read_b128 v[4:7], v72 offset:1664
	ds_read_b128 v[16:19], v72 offset:2432
	ds_read_b128 v[20:23], v72 offset:2816
	ds_read_b128 v[28:31], v72 offset:3584
	v_add_f32_dpp v64, v64, v64 quad_perm:[2,3,0,1] row_mask:0xf bank_mask:0xf bound_ctrl:1
	s_nop 1
	v_add_f32_dpp v64, v64, v64 row_half_mirror row_mask:0xf bank_mask:0xf bound_ctrl:1
	s_nop 1
	v_add_f32_dpp v64, v64, v64 row_mirror row_mask:0xf bank_mask:0xf bound_ctrl:1
	v_pk_fma_f32 v[66:67], v[24:25], v[64:65], v[36:37] op_sel_hi:[1,0,1]
	v_pk_fma_f32 v[64:65], v[26:27], v[64:65], v[38:39] op_sel_hi:[1,0,1]
	v_pk_mul_f32 v[88:89], v[48:49], v[66:67]
	v_pk_mul_f32 v[34:35], v[34:35], v[64:65]
	v_pk_mul_f32 v[42:43], v[42:43], v[64:65]
	v_pk_fma_f32 v[96:97], v[32:33], v[66:67], v[34:35]
	v_pk_fma_f32 v[66:67], v[40:41], v[66:67], v[42:43]
	v_pk_mul_f32 v[64:65], v[50:51], v[64:65]
	v_add_f32_e32 v66, v66, v67
	v_pk_fma_f32 v[88:89], v[52:53], v[90:91], v[88:89] op_sel_hi:[1,0,1]
	v_pk_fma_f32 v[64:65], v[54:55], v[90:91], v[64:65] op_sel_hi:[1,0,1]
	v_add_f32_dpp v66, v66, v66 quad_perm:[1,0,3,2] row_mask:0xf bank_mask:0xf bound_ctrl:1
	v_add_f32_e32 v90, v96, v97
	v_cndmask_b32_e32 v67, v75, v90, vcc
	v_add_f32_dpp v66, v66, v66 quad_perm:[2,3,0,1] row_mask:0xf bank_mask:0xf bound_ctrl:1
	v_cndmask_b32_e32 v75, v90, v75, vcc
	ds_read_b128 v[24:27], v72 offset:3072
	ds_read_b128 v[36:39], v72 offset:3328
	v_add_f32_dpp v66, v66, v66 row_half_mirror row_mask:0xf bank_mask:0xf bound_ctrl:1
	v_add_f32_dpp v75, v67, v75 quad_perm:[1,0,3,2] row_mask:0xf bank_mask:0xf bound_ctrl:1
	ds_read_b128 v[48:51], v72 offset:4736
	ds_read_b128 v[32:35], v72 offset:3840
	v_add_f32_dpp v66, v66, v66 row_mirror row_mask:0xf bank_mask:0xf bound_ctrl:1
	v_pk_fma_f32 v[64:65], v[46:47], v[66:67], v[64:65] op_sel_hi:[1,0,1]
	v_pk_fma_f32 v[88:89], v[44:45], v[66:67], v[88:89] op_sel_hi:[1,0,1]
	s_waitcnt lgkmcnt(11)
	v_pk_mul_f32 v[66:67], v[94:95], v[64:65]
	v_pk_mul_f32 v[58:59], v[58:59], v[64:65]
	v_pk_fma_f32 v[66:67], v[92:93], v[88:89], v[66:67]
	v_pk_mul_f32 v[64:65], v[78:79], v[64:65]
	v_add_f32_e32 v66, v66, v67
	v_pk_fma_f32 v[78:79], v[56:57], v[88:89], v[58:59]
	v_pk_mul_f32 v[76:77], v[76:77], v[88:89]
	v_add_f32_dpp v66, v66, v66 quad_perm:[1,0,3,2] row_mask:0xf bank_mask:0xf bound_ctrl:1
	v_pk_fma_f32 v[64:65], v[98:99], v[82:83], v[64:65] op_sel_hi:[0,1,1]
	v_add_f32_e32 v79, v78, v79
	v_add_f32_dpp v66, v66, v66 quad_perm:[2,3,0,1] row_mask:0xf bank_mask:0xf bound_ctrl:1
	v_pk_fma_f32 v[76:77], v[98:99], v[80:81], v[76:77] op_sel_hi:[0,1,1]
	ds_read_b128 v[40:43], v72 offset:4224
	ds_read_b128 v[52:55], v72 offset:4992
	v_add_f32_dpp v66, v66, v66 row_half_mirror row_mask:0xf bank_mask:0xf bound_ctrl:1
	ds_read_b128 v[44:47], v72 offset:4480
	ds_read_b128 v[56:59], v72 offset:5248
	v_add_f32_dpp v78, v66, v66 row_mirror row_mask:0xf bank_mask:0xf bound_ctrl:1
	v_pk_fma_f32 v[64:65], v[62:63], v[78:79], v[64:65] op_sel_hi:[1,0,1]
	v_pk_fma_f32 v[66:67], v[60:61], v[78:79], v[76:77] op_sel_hi:[1,0,1]
	v_pk_mul_f32 v[60:61], v[86:87], v[64:65]
	v_pk_fma_f32 v[60:61], v[84:85], v[66:67], v[60:61]
	s_nop 0
	v_add_f32_e32 v60, v60, v61
	v_cndmask_b32_e32 v61, v79, v60, vcc
	v_cndmask_b32_e32 v60, v60, v79, vcc
	s_nop 1
	v_add_f32_dpp v60, v61, v60 quad_perm:[1,0,3,2] row_mask:0xf bank_mask:0xf bound_ctrl:1
	v_cndmask_b32_e64 v61, v75, v60, s[4:5]
	v_cndmask_b32_e64 v60, v60, v75, s[4:5]
	s_nop 1
	v_add_f32_dpp v60, v61, v60 quad_perm:[2,3,0,1] row_mask:0xf bank_mask:0xf bound_ctrl:1
	s_nop 1
	v_add_f32_dpp v60, v60, v60 row_ror:4 row_mask:0xf bank_mask:0xf bound_ctrl:1
	s_nop 1
	v_add_f32_dpp v60, v60, v60 row_ror:8 row_mask:0xf bank_mask:0xf bound_ctrl:1
	ds_write_b32 v73, v60
	s_waitcnt lgkmcnt(14)
; template <int CTRL> DI float dppf(float v) { return __int_as_float(__builtin_amdgcn_update_dpp(0, __float_as_int(v), CTRL, 0xf, 0xf, false)); }
; DI float red16(float p) { p += dppf<0xB1>(p); p += dppf<0x4E>(p); p += dppf<0x141>(p); p += dppf<0x140>(p); return p; }
; DI void scan_task(const Params& P, int sb, unsigned char* lds) {
;     ...
;       for (int g4 = 0; g4 < CH / 4; ++g4) {
;         const float* gb = cb + g4 * 4 * SREC;
;         const float4 v4 = *(const float4*)(vrow + g4 * 4);
;         float pp[4];
; #pragma unroll
;         for (int i = 0; i < 4; ++i) {
;           ld_ops(nx3, gb + (i + 3) * SREC, q4);
;           const f2 a01 = {cur.a.x, cur.a.y}, a23 = {cur.a.z, cur.a.w}, w01 = {cur.w.x, cur.w.y}, w23 = {cur.w.z, cur.w.w};
;           const f2 k01 = {cur.k.x, cur.k.y}, k23 = {cur.k.z, cur.k.w}, b01 = {cur.b.x, cur.b.y}, b23 = {cur.b.z, cur.b.w};
;           const f2 r01 = {cur.r.x, cur.r.y}, r23 = {cur.r.z, cur.r.w};
;           f2 pa = S0 * a01; pa += S1 * a23;
;           const float vs = (i == 0) ? v4.x : (i == 1) ? v4.y : (i == 2) ? v4.z : v4.w;
;           const f2 vv = {vs, vs};
;           const f2 t0 = S0 * w01 + vv * k01, t1 = S1 * w23 + vv * k23;
;           const float sa = red16(pa.x + pa.y);
;           const f2 sa2 = {sa, sa};
;           S0 = t0 + sa2 * b01; S1 = t1 + sa2 * b23;
;           f2 py = S0 * r01; py += S1 * r23;
;           pp[i] = py.x + py.y;
;           cur = nxt; nxt = nx2; nx2 = nx3;
;         }
;         const float tA = o1 ? pp[0] : pp[1], kA = o1 ? pp[1] : pp[0];
;         const float tB = o1 ? pp[2] : pp[3], kB = o1 ? pp[3] : pp[2];
;         const float r0 = kA + dppf<0xB1>(tA), r1 = kB + dppf<0xB1>(tB);
;         const float tC = o2 ? r0 : r1, kC = o2 ? r1 : r0;
;         float u = kC + dppf<0x4E>(tC);
;         u += dppf<0x124>(u);
;         u += dppf<0x128>(u);
;         yb[(g4 * 4 + (q & 3)) * 16 + rowl] = u;
	v_pk_mul_f32 v[2:3], v[64:65], v[2:3]
	ds_read_b128 v[60:63], v72 offset:5888
	ds_read_b128 v[76:79], v72 offset:6144
	ds_read_b128 v[80:83], v72 offset:6400
	ds_read_b128 v[84:87], v72 offset:6656
	ds_read_b128 v[88:91], v100 offset:16
	ds_read_b128 v[92:95], v72 offset:5632
	v_pk_fma_f32 v[96:97], v[66:67], v[0:1], v[2:3]
	ds_read_b128 v[0:3], v72 offset:7040
	v_add_f32_e32 v75, v96, v97
	s_waitcnt lgkmcnt(2)
	v_pk_mul_f32 v[14:15], v[14:15], v[88:89] op_sel_hi:[1,0]
	v_pk_mul_f32 v[12:13], v[12:13], v[88:89] op_sel_hi:[1,0]
	v_add_f32_dpp v75, v75, v75 quad_perm:[1,0,3,2] row_mask:0xf bank_mask:0xf bound_ctrl:1
	v_pk_fma_f32 v[64:65], v[64:65], v[10:11], v[14:15]
	v_pk_fma_f32 v[66:67], v[66:67], v[8:9], v[12:13]
	v_add_f32_dpp v75, v75, v75 quad_perm:[2,3,0,1] row_mask:0xf bank_mask:0xf bound_ctrl:1
	v_mov_b32_e32 v98, v91
	ds_read_b128 v[8:11], v72 offset:7552
	ds_read_b128 v[12:15], v72 offset:7808
	v_add_f32_dpp v75, v75, v75 row_half_mirror row_mask:0xf bank_mask:0xf bound_ctrl:1
	s_nop 1
	v_add_f32_dpp v96, v75, v75 row_mirror row_mask:0xf bank_mask:0xf bound_ctrl:1
	v_pk_fma_f32 v[64:65], v[6:7], v[96:97], v[64:65] op_sel_hi:[1,0,1]
	v_pk_fma_f32 v[66:67], v[4:5], v[96:97], v[66:67] op_sel_hi:[1,0,1]
	v_pk_mul_f32 v[18:19], v[18:19], v[64:65]
	v_pk_mul_f32 v[22:23], v[22:23], v[64:65]
	v_pk_mul_f32 v[36:37], v[36:37], v[66:67]
	v_pk_mul_f32 v[38:39], v[38:39], v[64:65]
	v_pk_fma_f32 v[64:65], v[16:17], v[66:67], v[18:19]
	v_pk_fma_f32 v[66:67], v[20:21], v[66:67], v[22:23]
	v_add_f32_e32 v75, v64, v65
	v_add_f32_e32 v64, v66, v67
	v_pk_fma_f32 v[36:37], v[28:29], v[88:89], v[36:37] op_sel:[0,1,0]
	v_pk_fma_f32 v[38:39], v[30:31], v[88:89], v[38:39] op_sel:[0,1,0]
	v_add_f32_dpp v64, v64, v64 quad_perm:[1,0,3,2] row_mask:0xf bank_mask:0xf bound_ctrl:1
	ds_read_b128 v[4:7], v72 offset:7296
	ds_read_b128 v[16:19], v72 offset:8064
	ds_read_b128 v[20:23], v72 offset:8448
	ds_read_b128 v[28:31], v72 offset:9216
	v_add_f32_dpp v64, v64, v64 quad_perm:[2,3,0,1] row_mask:0xf bank_mask:0xf bound_ctrl:1
	s_nop 1
	v_add_f32_dpp v64, v64, v64 row_half_mirror row_mask:0xf bank_mask:0xf bound_ctrl:1
	s_nop 1
	v_add_f32_dpp v64, v64, v64 row_mirror row_mask:0xf bank_mask:0xf bound_ctrl:1
	v_pk_fma_f32 v[66:67], v[24:25], v[64:65], v[36:37] op_sel_hi:[1,0,1]
	v_pk_fma_f32 v[64:65], v[26:27], v[64:65], v[38:39] op_sel_hi:[1,0,1]
	v_pk_mul_f32 v[88:89], v[48:49], v[66:67]
	v_pk_mul_f32 v[34:35], v[34:35], v[64:65]
	v_pk_mul_f32 v[42:43], v[42:43], v[64:65]
	v_pk_fma_f32 v[96:97], v[32:33], v[66:67], v[34:35]
	v_pk_fma_f32 v[66:67], v[40:41], v[66:67], v[42:43]
	v_pk_mul_f32 v[64:65], v[50:51], v[64:65]
	v_add_f32_e32 v66, v66, v67
	v_pk_fma_f32 v[88:89], v[52:53], v[90:91], v[88:89] op_sel_hi:[1,0,1]
	v_pk_fma_f32 v[64:65], v[54:55], v[90:91], v[64:65] op_sel_hi:[1,0,1]
	v_add_f32_dpp v66, v66, v66 quad_perm:[1,0,3,2] row_mask:0xf bank_mask:0xf bound_ctrl:1
	v_add_f32_e32 v90, v96, v97
	v_cndmask_b32_e32 v67, v75, v90, vcc
	v_add_f32_dpp v66, v66, v66 quad_perm:[2,3,0,1] row_mask:0xf bank_mask:0xf bound_ctrl:1
	v_cndmask_b32_e32 v75, v90, v75, vcc
	ds_read_b128 v[24:27], v72 offset:8704
	ds_read_b128 v[36:39], v72 offset:8960
	v_add_f32_dpp v66, v66, v66 row_half_mirror row_mask:0xf bank_mask:0xf bound_ctrl:1
	v_add_f32_dpp v75, v67, v75 quad_perm:[1,0,3,2] row_mask:0xf bank_mask:0xf bound_ctrl:1
	ds_read_b128 v[48:51], v72 offset:10368
	ds_read_b128 v[32:35], v72 offset:9472
	v_add_f32_dpp v66, v66, v66 row_mirror row_mask:0xf bank_mask:0xf bound_ctrl:1
	v_pk_fma_f32 v[64:65], v[46:47], v[66:67], v[64:65] op_sel_hi:[1,0,1]
	v_pk_fma_f32 v[88:89], v[44:45], v[66:67], v[88:89] op_sel_hi:[1,0,1]
	s_waitcnt lgkmcnt(11)
	v_pk_mul_f32 v[66:67], v[94:95], v[64:65]
	v_pk_mul_f32 v[58:59], v[58:59], v[64:65]
	v_pk_fma_f32 v[66:67], v[92:93], v[88:89], v[66:67]
	v_pk_mul_f32 v[64:65], v[78:79], v[64:65]
	v_add_f32_e32 v66, v66, v67
	v_pk_fma_f32 v[78:79], v[56:57], v[88:89], v[58:59]
	v_pk_mul_f32 v[76:77], v[76:77], v[88:89]
	v_add_f32_dpp v66, v66, v66 quad_perm:[1,0,3,2] row_mask:0xf bank_mask:0xf bound_ctrl:1
	v_pk_fma_f32 v[64:65], v[98:99], v[82:83], v[64:65] op_sel_hi:[0,1,1]
	v_add_f32_e32 v79, v78, v79
	v_add_f32_dpp v66, v66, v66 quad_perm:[2,3,0,1] row_mask:0xf bank_mask:0xf bound_ctrl:1
	v_pk_fma_f32 v[76:77], v[98:99], v[80:81], v[76:77] op_sel_hi:[0,1,1]
	ds_read_b128 v[40:43], v72 offset:9856
	ds_read_b128 v[52:55], v72 offset:10624
	v_add_f32_dpp v66, v66, v66 row_half_mirror row_mask:0xf bank_mask:0xf bound_ctrl:1
	ds_read_b128 v[44:47], v72 offset:10112
	ds_read_b128 v[56:59], v72 offset:10880
	v_add_f32_dpp v78, v66, v66 row_mirror row_mask:0xf bank_mask:0xf bound_ctrl:1
	v_pk_fma_f32 v[64:65], v[62:63], v[78:79], v[64:65] op_sel_hi:[1,0,1]
	v_pk_fma_f32 v[66:67], v[60:61], v[78:79], v[76:77] op_sel_hi:[1,0,1]
	v_pk_mul_f32 v[60:61], v[86:87], v[64:65]
	v_pk_fma_f32 v[60:61], v[84:85], v[66:67], v[60:61]
	s_nop 0
	v_add_f32_e32 v60, v60, v61
	v_cndmask_b32_e32 v61, v79, v60, vcc
	v_cndmask_b32_e32 v60, v60, v79, vcc
	s_nop 1
	v_add_f32_dpp v60, v61, v60 quad_perm:[1,0,3,2] row_mask:0xf bank_mask:0xf bound_ctrl:1
	v_cndmask_b32_e64 v61, v75, v60, s[4:5]
	v_cndmask_b32_e64 v60, v60, v75, s[4:5]
	s_nop 1
	v_add_f32_dpp v60, v61, v60 quad_perm:[2,3,0,1] row_mask:0xf bank_mask:0xf bound_ctrl:1
	s_nop 1
	v_add_f32_dpp v60, v60, v60 row_ror:4 row_mask:0xf bank_mask:0xf bound_ctrl:1
	s_nop 1
	v_add_f32_dpp v60, v60, v60 row_ror:8 row_mask:0xf bank_mask:0xf bound_ctrl:1
	ds_write_b32 v73, v60 offset:256
	s_waitcnt lgkmcnt(14)
; template <int CTRL> DI float dppf(float v) { return __int_as_float(__builtin_amdgcn_update_dpp(0, __float_as_int(v), CTRL, 0xf, 0xf, false)); }
; DI float red16(float p) { p += dppf<0xB1>(p); p += dppf<0x4E>(p); p += dppf<0x141>(p); p += dppf<0x140>(p); return p; }
; DI void scan_task(const Params& P, int sb, unsigned char* lds) {
;     ...
;       for (int g4 = 0; g4 < CH / 4; ++g4) {
;         const float* gb = cb + g4 * 4 * SREC;
;         const float4 v4 = *(const float4*)(vrow + g4 * 4);
;         float pp[4];
; #pragma unroll
;         for (int i = 0; i < 4; ++i) {
;           ld_ops(nx3, gb + (i + 3) * SREC, q4);
;           const f2 a01 = {cur.a.x, cur.a.y}, a23 = {cur.a.z, cur.a.w}, w01 = {cur.w.x, cur.w.y}, w23 = {cur.w.z, cur.w.w};
;           const f2 k01 = {cur.k.x, cur.k.y}, k23 = {cur.k.z, cur.k.w}, b01 = {cur.b.x, cur.b.y}, b23 = {cur.b.z, cur.b.w};
;           const f2 r01 = {cur.r.x, cur.r.y}, r23 = {cur.r.z, cur.r.w};
;           f2 pa = S0 * a01; pa += S1 * a23;
;           const float vs = (i == 0) ? v4.x : (i == 1) ? v4.y : (i == 2) ? v4.z : v4.w;
;           const f2 vv = {vs, vs};
;           const f2 t0 = S0 * w01 + vv * k01, t1 = S1 * w23 + vv * k23;
;           const float sa = red16(pa.x + pa.y);
;           const f2 sa2 = {sa, sa};
;           S0 = t0 + sa2 * b01; S1 = t1 + sa2 * b23;
;           f2 py = S0 * r01; py += S1 * r23;
;           pp[i] = py.x + py.y;
;           cur = nxt; nxt = nx2; nx2 = nx3;
;         }
;         const float tA = o1 ? pp[0] : pp[1], kA = o1 ? pp[1] : pp[0];
;         const float tB = o1 ? pp[2] : pp[3], kB = o1 ? pp[3] : pp[2];
;         const float r0 = kA + dppf<0xB1>(tA), r1 = kB + dppf<0xB1>(tB);
;         const float tC = o2 ? r0 : r1, kC = o2 ? r1 : r0;
;         float u = kC + dppf<0x4E>(tC);
;         u += dppf<0x124>(u);
;         u += dppf<0x128>(u);
;         yb[(g4 * 4 + (q & 3)) * 16 + rowl] = u;
	v_pk_mul_f32 v[2:3], v[64:65], v[2:3]
	ds_read_b128 v[60:63], v72 offset:11520
	ds_read_b128 v[76:79], v72 offset:11776
	ds_read_b128 v[80:83], v72 offset:12032
	ds_read_b128 v[84:87], v72 offset:12288
	ds_read_b128 v[88:91], v100 offset:32
	ds_read_b128 v[92:95], v72 offset:11264
	v_pk_fma_f32 v[96:97], v[66:67], v[0:1], v[2:3]
	ds_read_b128 v[0:3], v72 offset:12672
	v_add_f32_e32 v75, v96, v97
	s_waitcnt lgkmcnt(2)
	v_pk_mul_f32 v[14:15], v[14:15], v[88:89] op_sel_hi:[1,0]
	v_pk_mul_f32 v[12:13], v[12:13], v[88:89] op_sel_hi:[1,0]
	v_add_f32_dpp v75, v75, v75 quad_perm:[1,0,3,2] row_mask:0xf bank_mask:0xf bound_ctrl:1
	v_pk_fma_f32 v[64:65], v[64:65], v[10:11], v[14:15]
	v_pk_fma_f32 v[66:67], v[66:67], v[8:9], v[12:13]
	v_add_f32_dpp v75, v75, v75 quad_perm:[2,3,0,1] row_mask:0xf bank_mask:0xf bound_ctrl:1
	v_mov_b32_e32 v98, v91
	ds_read_b128 v[8:11], v72 offset:13184
	ds_read_b128 v[12:15], v72 offset:13440
	v_add_f32_dpp v75, v75, v75 row_half_mirror row_mask:0xf bank_mask:0xf bound_ctrl:1
	s_nop 1
	v_add_f32_dpp v96, v75, v75 row_mirror row_mask:0xf bank_mask:0xf bound_ctrl:1
	v_pk_fma_f32 v[64:65], v[6:7], v[96:97], v[64:65] op_sel_hi:[1,0,1]
	v_pk_fma_f32 v[66:67], v[4:5], v[96:97], v[66:67] op_sel_hi:[1,0,1]
	v_pk_mul_f32 v[18:19], v[18:19], v[64:65]
	v_pk_mul_f32 v[22:23], v[22:23], v[64:65]
	v_pk_mul_f32 v[36:37], v[36:37], v[66:67]
	v_pk_mul_f32 v[38:39], v[38:39], v[64:65]
	v_pk_fma_f32 v[64:65], v[16:17], v[66:67], v[18:19]
	v_pk_fma_f32 v[66:67], v[20:21], v[66:67], v[22:23]
	v_add_f32_e32 v75, v64, v65
	v_add_f32_e32 v64, v66, v67
	v_pk_fma_f32 v[36:37], v[28:29], v[88:89], v[36:37] op_sel:[0,1,0]
	v_pk_fma_f32 v[38:39], v[30:31], v[88:89], v[38:39] op_sel:[0,1,0]
	v_add_f32_dpp v64, v64, v64 quad_perm:[1,0,3,2] row_mask:0xf bank_mask:0xf bound_ctrl:1
	ds_read_b128 v[4:7], v72 offset:12928
	ds_read_b128 v[16:19], v72 offset:13696
	ds_read_b128 v[20:23], v72 offset:14080
	ds_read_b128 v[28:31], v72 offset:14848
	v_add_f32_dpp v64, v64, v64 quad_perm:[2,3,0,1] row_mask:0xf bank_mask:0xf bound_ctrl:1
	s_nop 1
	v_add_f32_dpp v64, v64, v64 row_half_mirror row_mask:0xf bank_mask:0xf bound_ctrl:1
	s_nop 1
	v_add_f32_dpp v64, v64, v64 row_mirror row_mask:0xf bank_mask:0xf bound_ctrl:1
	v_pk_fma_f32 v[66:67], v[24:25], v[64:65], v[36:37] op_sel_hi:[1,0,1]
	v_pk_fma_f32 v[64:65], v[26:27], v[64:65], v[38:39] op_sel_hi:[1,0,1]
	v_pk_mul_f32 v[88:89], v[48:49], v[66:67]
	v_pk_mul_f32 v[34:35], v[34:35], v[64:65]
	v_pk_mul_f32 v[42:43], v[42:43], v[64:65]
	v_pk_fma_f32 v[96:97], v[32:33], v[66:67], v[34:35]
	v_pk_fma_f32 v[66:67], v[40:41], v[66:67], v[42:43]
	v_pk_mul_f32 v[64:65], v[50:51], v[64:65]
	v_add_f32_e32 v66, v66, v67
	v_pk_fma_f32 v[88:89], v[52:53], v[90:91], v[88:89] op_sel_hi:[1,0,1]
	v_pk_fma_f32 v[64:65], v[54:55], v[90:91], v[64:65] op_sel_hi:[1,0,1]
	v_add_f32_dpp v66, v66, v66 quad_perm:[1,0,3,2] row_mask:0xf bank_mask:0xf bound_ctrl:1
	v_add_f32_e32 v90, v96, v97
	v_cndmask_b32_e32 v67, v75, v90, vcc
	v_add_f32_dpp v66, v66, v66 quad_perm:[2,3,0,1] row_mask:0xf bank_mask:0xf bound_ctrl:1
	v_cndmask_b32_e32 v75, v90, v75, vcc
	ds_read_b128 v[24:27], v72 offset:14336
	ds_read_b128 v[36:39], v72 offset:14592
	v_add_f32_dpp v66, v66, v66 row_half_mirror row_mask:0xf bank_mask:0xf bound_ctrl:1
	v_add_f32_dpp v75, v67, v75 quad_perm:[1,0,3,2] row_mask:0xf bank_mask:0xf bound_ctrl:1
	ds_read_b128 v[48:51], v72 offset:16000
	ds_read_b128 v[32:35], v72 offset:15104
	v_add_f32_dpp v66, v66, v66 row_mirror row_mask:0xf bank_mask:0xf bound_ctrl:1
	v_pk_fma_f32 v[64:65], v[46:47], v[66:67], v[64:65] op_sel_hi:[1,0,1]
	v_pk_fma_f32 v[88:89], v[44:45], v[66:67], v[88:89] op_sel_hi:[1,0,1]
	s_waitcnt lgkmcnt(11)
	v_pk_mul_f32 v[66:67], v[94:95], v[64:65]
	v_pk_mul_f32 v[58:59], v[58:59], v[64:65]
	v_pk_fma_f32 v[66:67], v[92:93], v[88:89], v[66:67]
	v_pk_mul_f32 v[64:65], v[78:79], v[64:65]
	v_add_f32_e32 v66, v66, v67
	v_pk_fma_f32 v[78:79], v[56:57], v[88:89], v[58:59]
	v_pk_mul_f32 v[76:77], v[76:77], v[88:89]
	v_add_f32_dpp v66, v66, v66 quad_perm:[1,0,3,2] row_mask:0xf bank_mask:0xf bound_ctrl:1
	v_pk_fma_f32 v[64:65], v[98:99], v[82:83], v[64:65] op_sel_hi:[0,1,1]
	v_add_f32_e32 v79, v78, v79
	v_add_f32_dpp v66, v66, v66 quad_perm:[2,3,0,1] row_mask:0xf bank_mask:0xf bound_ctrl:1
	v_pk_fma_f32 v[76:77], v[98:99], v[80:81], v[76:77] op_sel_hi:[0,1,1]
	ds_read_b128 v[40:43], v72 offset:15488
	ds_read_b128 v[52:55], v72 offset:16256
	v_add_f32_dpp v66, v66, v66 row_half_mirror row_mask:0xf bank_mask:0xf bound_ctrl:1
	ds_read_b128 v[44:47], v72 offset:15744
	ds_read_b128 v[56:59], v72 offset:16512
	v_add_f32_dpp v78, v66, v66 row_mirror row_mask:0xf bank_mask:0xf bound_ctrl:1
	v_pk_fma_f32 v[64:65], v[62:63], v[78:79], v[64:65] op_sel_hi:[1,0,1]
	v_pk_fma_f32 v[66:67], v[60:61], v[78:79], v[76:77] op_sel_hi:[1,0,1]
	v_pk_mul_f32 v[60:61], v[86:87], v[64:65]
	v_pk_fma_f32 v[60:61], v[84:85], v[66:67], v[60:61]
	s_nop 0
	v_add_f32_e32 v60, v60, v61
	v_cndmask_b32_e32 v61, v79, v60, vcc
	v_cndmask_b32_e32 v60, v60, v79, vcc
	s_nop 1
	v_add_f32_dpp v60, v61, v60 quad_perm:[1,0,3,2] row_mask:0xf bank_mask:0xf bound_ctrl:1
	v_cndmask_b32_e64 v61, v75, v60, s[4:5]
	v_cndmask_b32_e64 v60, v60, v75, s[4:5]
	s_nop 1
	v_add_f32_dpp v60, v61, v60 quad_perm:[2,3,0,1] row_mask:0xf bank_mask:0xf bound_ctrl:1
	s_nop 1
	v_add_f32_dpp v60, v60, v60 row_ror:4 row_mask:0xf bank_mask:0xf bound_ctrl:1
	s_nop 1
	v_add_f32_dpp v60, v60, v60 row_ror:8 row_mask:0xf bank_mask:0xf bound_ctrl:1
	ds_write_b32 v73, v60 offset:512
	s_waitcnt lgkmcnt(14)
; template <int CTRL> DI float dppf(float v) { return __int_as_float(__builtin_amdgcn_update_dpp(0, __float_as_int(v), CTRL, 0xf, 0xf, false)); }
; DI float red16(float p) { p += dppf<0xB1>(p); p += dppf<0x4E>(p); p += dppf<0x141>(p); p += dppf<0x140>(p); return p; }
; DI void scan_task(const Params& P, int sb, unsigned char* lds) {
;     ...
;       for (int g4 = 0; g4 < CH / 4; ++g4) {
;         const float* gb = cb + g4 * 4 * SREC;
;         const float4 v4 = *(const float4*)(vrow + g4 * 4);
;         float pp[4];
; #pragma unroll
;         for (int i = 0; i < 4; ++i) {
;           ld_ops(nx3, gb + (i + 3) * SREC, q4);
;           const f2 a01 = {cur.a.x, cur.a.y}, a23 = {cur.a.z, cur.a.w}, w01 = {cur.w.x, cur.w.y}, w23 = {cur.w.z, cur.w.w};
;           const f2 k01 = {cur.k.x, cur.k.y}, k23 = {cur.k.z, cur.k.w}, b01 = {cur.b.x, cur.b.y}, b23 = {cur.b.z, cur.b.w};
;           const f2 r01 = {cur.r.x, cur.r.y}, r23 = {cur.r.z, cur.r.w};
;           f2 pa = S0 * a01; pa += S1 * a23;
;           const float vs = (i == 0) ? v4.x : (i == 1) ? v4.y : (i == 2) ? v4.z : v4.w;
;           const f2 vv = {vs, vs};
;           const f2 t0 = S0 * w01 + vv * k01, t1 = S1 * w23 + vv * k23;
;           const float sa = red16(pa.x + pa.y);
;           const f2 sa2 = {sa, sa};
;           S0 = t0 + sa2 * b01; S1 = t1 + sa2 * b23;
;           f2 py = S0 * r01; py += S1 * r23;
;           pp[i] = py.x + py.y;
;           cur = nxt; nxt = nx2; nx2 = nx3;
;         }
;         const float tA = o1 ? pp[0] : pp[1], kA = o1 ? pp[1] : pp[0];
;         const float tB = o1 ? pp[2] : pp[3], kB = o1 ? pp[3] : pp[2];
;         const float r0 = kA + dppf<0xB1>(tA), r1 = kB + dppf<0xB1>(tB);
;         const float tC = o2 ? r0 : r1, kC = o2 ? r1 : r0;
;         float u = kC + dppf<0x4E>(tC);
;         u += dppf<0x124>(u);
;         u += dppf<0x128>(u);
;         yb[(g4 * 4 + (q & 3)) * 16 + rowl] = u;
	v_pk_mul_f32 v[2:3], v[64:65], v[2:3]
	ds_read_b128 v[60:63], v72 offset:17152
	ds_read_b128 v[76:79], v72 offset:17408
	ds_read_b128 v[80:83], v72 offset:17664
	ds_read_b128 v[84:87], v72 offset:17920
	ds_read_b128 v[88:91], v100 offset:48
	ds_read_b128 v[92:95], v72 offset:16896
	v_pk_fma_f32 v[96:97], v[66:67], v[0:1], v[2:3]
	ds_read_b128 v[0:3], v72 offset:18304
	v_add_f32_e32 v75, v96, v97
	s_waitcnt lgkmcnt(2)
	v_pk_mul_f32 v[14:15], v[14:15], v[88:89] op_sel_hi:[1,0]
	v_pk_mul_f32 v[12:13], v[12:13], v[88:89] op_sel_hi:[1,0]
	v_add_f32_dpp v75, v75, v75 quad_perm:[1,0,3,2] row_mask:0xf bank_mask:0xf bound_ctrl:1
	v_pk_fma_f32 v[64:65], v[64:65], v[10:11], v[14:15]
	v_pk_fma_f32 v[66:67], v[66:67], v[8:9], v[12:13]
	v_add_f32_dpp v75, v75, v75 quad_perm:[2,3,0,1] row_mask:0xf bank_mask:0xf bound_ctrl:1
	v_mov_b32_e32 v98, v91
	ds_read_b128 v[8:11], v72 offset:18816
	ds_read_b128 v[12:15], v72 offset:19072
	v_add_f32_dpp v75, v75, v75 row_half_mirror row_mask:0xf bank_mask:0xf bound_ctrl:1
	s_nop 1
	v_add_f32_dpp v96, v75, v75 row_mirror row_mask:0xf bank_mask:0xf bound_ctrl:1
	v_pk_fma_f32 v[64:65], v[6:7], v[96:97], v[64:65] op_sel_hi:[1,0,1]
	v_pk_fma_f32 v[66:67], v[4:5], v[96:97], v[66:67] op_sel_hi:[1,0,1]
	v_pk_mul_f32 v[18:19], v[18:19], v[64:65]
	v_pk_mul_f32 v[22:23], v[22:23], v[64:65]
	v_pk_mul_f32 v[36:37], v[36:37], v[66:67]
	v_pk_mul_f32 v[38:39], v[38:39], v[64:65]
	v_pk_fma_f32 v[64:65], v[16:17], v[66:67], v[18:19]
	v_pk_fma_f32 v[66:67], v[20:21], v[66:67], v[22:23]
	v_add_f32_e32 v75, v64, v65
	v_add_f32_e32 v64, v66, v67
	v_pk_fma_f32 v[36:37], v[28:29], v[88:89], v[36:37] op_sel:[0,1,0]
	v_pk_fma_f32 v[38:39], v[30:31], v[88:89], v[38:39] op_sel:[0,1,0]
	v_add_f32_dpp v64, v64, v64 quad_perm:[1,0,3,2] row_mask:0xf bank_mask:0xf bound_ctrl:1
	ds_read_b128 v[4:7], v72 offset:18560
	ds_read_b128 v[16:19], v72 offset:19328
	ds_read_b128 v[20:23], v72 offset:19712
	ds_read_b128 v[28:31], v72 offset:20480
	v_add_f32_dpp v64, v64, v64 quad_perm:[2,3,0,1] row_mask:0xf bank_mask:0xf bound_ctrl:1
	s_nop 1
	v_add_f32_dpp v64, v64, v64 row_half_mirror row_mask:0xf bank_mask:0xf bound_ctrl:1
	s_nop 1
	v_add_f32_dpp v64, v64, v64 row_mirror row_mask:0xf bank_mask:0xf bound_ctrl:1
	v_pk_fma_f32 v[66:67], v[24:25], v[64:65], v[36:37] op_sel_hi:[1,0,1]
	v_pk_fma_f32 v[64:65], v[26:27], v[64:65], v[38:39] op_sel_hi:[1,0,1]
	v_pk_mul_f32 v[88:89], v[48:49], v[66:67]
	v_pk_mul_f32 v[34:35], v[34:35], v[64:65]
	v_pk_mul_f32 v[42:43], v[42:43], v[64:65]
	v_pk_fma_f32 v[96:97], v[32:33], v[66:67], v[34:35]
	v_pk_fma_f32 v[66:67], v[40:41], v[66:67], v[42:43]
	v_pk_mul_f32 v[64:65], v[50:51], v[64:65]
	v_add_f32_e32 v66, v66, v67
	v_pk_fma_f32 v[88:89], v[52:53], v[90:91], v[88:89] op_sel_hi:[1,0,1]
	v_pk_fma_f32 v[64:65], v[54:55], v[90:91], v[64:65] op_sel_hi:[1,0,1]
	v_add_f32_dpp v66, v66, v66 quad_perm:[1,0,3,2] row_mask:0xf bank_mask:0xf bound_ctrl:1
	v_add_f32_e32 v90, v96, v97
	v_cndmask_b32_e32 v67, v75, v90, vcc
	v_add_f32_dpp v66, v66, v66 quad_perm:[2,3,0,1] row_mask:0xf bank_mask:0xf bound_ctrl:1
	v_cndmask_b32_e32 v75, v90, v75, vcc
	ds_read_b128 v[24:27], v72 offset:19968
	ds_read_b128 v[36:39], v72 offset:20224
	v_add_f32_dpp v66, v66, v66 row_half_mirror row_mask:0xf bank_mask:0xf bound_ctrl:1
	v_add_f32_dpp v75, v67, v75 quad_perm:[1,0,3,2] row_mask:0xf bank_mask:0xf bound_ctrl:1
	ds_read_b128 v[48:51], v72 offset:21632
	ds_read_b128 v[32:35], v72 offset:20736
	v_add_f32_dpp v66, v66, v66 row_mirror row_mask:0xf bank_mask:0xf bound_ctrl:1
	v_pk_fma_f32 v[64:65], v[46:47], v[66:67], v[64:65] op_sel_hi:[1,0,1]
	v_pk_fma_f32 v[88:89], v[44:45], v[66:67], v[88:89] op_sel_hi:[1,0,1]
	s_waitcnt lgkmcnt(11)
	v_pk_mul_f32 v[66:67], v[94:95], v[64:65]
	v_pk_mul_f32 v[58:59], v[58:59], v[64:65]
	v_pk_fma_f32 v[66:67], v[92:93], v[88:89], v[66:67]
	v_pk_mul_f32 v[64:65], v[78:79], v[64:65]
	v_add_f32_e32 v66, v66, v67
	v_pk_fma_f32 v[78:79], v[56:57], v[88:89], v[58:59]
	v_pk_mul_f32 v[76:77], v[76:77], v[88:89]
	v_add_f32_dpp v66, v66, v66 quad_perm:[1,0,3,2] row_mask:0xf bank_mask:0xf bound_ctrl:1
	v_pk_fma_f32 v[64:65], v[98:99], v[82:83], v[64:65] op_sel_hi:[0,1,1]
	v_add_f32_e32 v79, v78, v79
	v_add_f32_dpp v66, v66, v66 quad_perm:[2,3,0,1] row_mask:0xf bank_mask:0xf bound_ctrl:1
	v_pk_fma_f32 v[76:77], v[98:99], v[80:81], v[76:77] op_sel_hi:[0,1,1]
	ds_read_b128 v[40:43], v72 offset:21120
	ds_read_b128 v[52:55], v72 offset:21888
	v_add_f32_dpp v66, v66, v66 row_half_mirror row_mask:0xf bank_mask:0xf bound_ctrl:1
	ds_read_b128 v[44:47], v72 offset:21376
	ds_read_b128 v[56:59], v72 offset:22144
	v_add_f32_dpp v78, v66, v66 row_mirror row_mask:0xf bank_mask:0xf bound_ctrl:1
	v_pk_fma_f32 v[64:65], v[62:63], v[78:79], v[64:65] op_sel_hi:[1,0,1]
	v_pk_fma_f32 v[66:67], v[60:61], v[78:79], v[76:77] op_sel_hi:[1,0,1]
	v_pk_mul_f32 v[60:61], v[86:87], v[64:65]
	v_pk_fma_f32 v[60:61], v[84:85], v[66:67], v[60:61]
	s_nop 0
	v_add_f32_e32 v60, v60, v61
	v_cndmask_b32_e32 v61, v79, v60, vcc
	v_cndmask_b32_e32 v60, v60, v79, vcc
	s_nop 1
	v_add_f32_dpp v60, v61, v60 quad_perm:[1,0,3,2] row_mask:0xf bank_mask:0xf bound_ctrl:1
	v_cndmask_b32_e64 v61, v75, v60, s[4:5]
	v_cndmask_b32_e64 v60, v60, v75, s[4:5]
	s_nop 1
	v_add_f32_dpp v60, v61, v60 quad_perm:[2,3,0,1] row_mask:0xf bank_mask:0xf bound_ctrl:1
	s_nop 1
	v_add_f32_dpp v60, v60, v60 row_ror:4 row_mask:0xf bank_mask:0xf bound_ctrl:1
	s_nop 1
	v_add_f32_dpp v60, v60, v60 row_ror:8 row_mask:0xf bank_mask:0xf bound_ctrl:1
	ds_write_b32 v73, v60 offset:768
	s_waitcnt lgkmcnt(14)
; template <int CTRL> DI float dppf(float v) { return __int_as_float(__builtin_amdgcn_update_dpp(0, __float_as_int(v), CTRL, 0xf, 0xf, false)); }
; DI float red16(float p) { p += dppf<0xB1>(p); p += dppf<0x4E>(p); p += dppf<0x141>(p); p += dppf<0x140>(p); return p; }
; DI void scan_task(const Params& P, int sb, unsigned char* lds) {
;     ...
;       for (int g4 = 0; g4 < CH / 4; ++g4) {
;         const float* gb = cb + g4 * 4 * SREC;
;         const float4 v4 = *(const float4*)(vrow + g4 * 4);
;         float pp[4];
; #pragma unroll
;         for (int i = 0; i < 4; ++i) {
;           ld_ops(nx3, gb + (i + 3) * SREC, q4);
;           const f2 a01 = {cur.a.x, cur.a.y}, a23 = {cur.a.z, cur.a.w}, w01 = {cur.w.x, cur.w.y}, w23 = {cur.w.z, cur.w.w};
;           const f2 k01 = {cur.k.x, cur.k.y}, k23 = {cur.k.z, cur.k.w}, b01 = {cur.b.x, cur.b.y}, b23 = {cur.b.z, cur.b.w};
;           const f2 r01 = {cur.r.x, cur.r.y}, r23 = {cur.r.z, cur.r.w};
;           f2 pa = S0 * a01; pa += S1 * a23;
;           const float vs = (i == 0) ? v4.x : (i == 1) ? v4.y : (i == 2) ? v4.z : v4.w;
;           const f2 vv = {vs, vs};
;           const f2 t0 = S0 * w01 + vv * k01, t1 = S1 * w23 + vv * k23;
;           const float sa = red16(pa.x + pa.y);
;           const f2 sa2 = {sa, sa};
;           S0 = t0 + sa2 * b01; S1 = t1 + sa2 * b23;
;           f2 py = S0 * r01; py += S1 * r23;
;           pp[i] = py.x + py.y;
;           cur = nxt; nxt = nx2; nx2 = nx3;
;         }
;         const float tA = o1 ? pp[0] : pp[1], kA = o1 ? pp[1] : pp[0];
;         const float tB = o1 ? pp[2] : pp[3], kB = o1 ? pp[3] : pp[2];
;         const float r0 = kA + dppf<0xB1>(tA), r1 = kB + dppf<0xB1>(tB);
;         const float tC = o2 ? r0 : r1, kC = o2 ? r1 : r0;
;         float u = kC + dppf<0x4E>(tC);
;         u += dppf<0x124>(u);
;         u += dppf<0x128>(u);
;         yb[(g4 * 4 + (q & 3)) * 16 + rowl] = u;
	v_pk_mul_f32 v[2:3], v[64:65], v[2:3]
	ds_read_b128 v[60:63], v72 offset:22784
	ds_read_b128 v[76:79], v72 offset:23040
	ds_read_b128 v[80:83], v72 offset:23296
	ds_read_b128 v[84:87], v72 offset:23552
	ds_read_b128 v[88:91], v100 offset:64
	ds_read_b128 v[92:95], v72 offset:22528
	v_pk_fma_f32 v[96:97], v[66:67], v[0:1], v[2:3]
	ds_read_b128 v[0:3], v72 offset:23936
	v_add_f32_e32 v75, v96, v97
	s_waitcnt lgkmcnt(2)
	v_pk_mul_f32 v[14:15], v[14:15], v[88:89] op_sel_hi:[1,0]
	v_pk_mul_f32 v[12:13], v[12:13], v[88:89] op_sel_hi:[1,0]
	v_add_f32_dpp v75, v75, v75 quad_perm:[1,0,3,2] row_mask:0xf bank_mask:0xf bound_ctrl:1
	v_pk_fma_f32 v[64:65], v[64:65], v[10:11], v[14:15]
	v_pk_fma_f32 v[66:67], v[66:67], v[8:9], v[12:13]
	v_add_f32_dpp v75, v75, v75 quad_perm:[2,3,0,1] row_mask:0xf bank_mask:0xf bound_ctrl:1
	v_mov_b32_e32 v98, v91
	ds_read_b128 v[8:11], v72 offset:24448
	ds_read_b128 v[12:15], v72 offset:24704
	v_add_f32_dpp v75, v75, v75 row_half_mirror row_mask:0xf bank_mask:0xf bound_ctrl:1
	s_nop 1
	v_add_f32_dpp v96, v75, v75 row_mirror row_mask:0xf bank_mask:0xf bound_ctrl:1
	v_pk_fma_f32 v[64:65], v[6:7], v[96:97], v[64:65] op_sel_hi:[1,0,1]
	v_pk_fma_f32 v[66:67], v[4:5], v[96:97], v[66:67] op_sel_hi:[1,0,1]
	v_pk_mul_f32 v[18:19], v[18:19], v[64:65]
	v_pk_mul_f32 v[22:23], v[22:23], v[64:65]
	v_pk_mul_f32 v[36:37], v[36:37], v[66:67]
	v_pk_mul_f32 v[38:39], v[38:39], v[64:65]
	v_pk_fma_f32 v[64:65], v[16:17], v[66:67], v[18:19]
	v_pk_fma_f32 v[66:67], v[20:21], v[66:67], v[22:23]
	v_add_f32_e32 v75, v64, v65
	v_add_f32_e32 v64, v66, v67
	v_pk_fma_f32 v[36:37], v[28:29], v[88:89], v[36:37] op_sel:[0,1,0]
	v_pk_fma_f32 v[38:39], v[30:31], v[88:89], v[38:39] op_sel:[0,1,0]
	v_add_f32_dpp v64, v64, v64 quad_perm:[1,0,3,2] row_mask:0xf bank_mask:0xf bound_ctrl:1
	ds_read_b128 v[4:7], v72 offset:24192
	ds_read_b128 v[16:19], v72 offset:24960
	ds_read_b128 v[20:23], v72 offset:25344
	ds_read_b128 v[28:31], v72 offset:26112
	v_add_f32_dpp v64, v64, v64 quad_perm:[2,3,0,1] row_mask:0xf bank_mask:0xf bound_ctrl:1
	s_nop 1
	v_add_f32_dpp v64, v64, v64 row_half_mirror row_mask:0xf bank_mask:0xf bound_ctrl:1
	s_nop 1
	v_add_f32_dpp v64, v64, v64 row_mirror row_mask:0xf bank_mask:0xf bound_ctrl:1
	v_pk_fma_f32 v[66:67], v[24:25], v[64:65], v[36:37] op_sel_hi:[1,0,1]
	v_pk_fma_f32 v[64:65], v[26:27], v[64:65], v[38:39] op_sel_hi:[1,0,1]
	v_pk_mul_f32 v[88:89], v[48:49], v[66:67]
	v_pk_mul_f32 v[34:35], v[34:35], v[64:65]
	v_pk_mul_f32 v[42:43], v[42:43], v[64:65]
	v_pk_fma_f32 v[96:97], v[32:33], v[66:67], v[34:35]
	v_pk_fma_f32 v[66:67], v[40:41], v[66:67], v[42:43]
	v_pk_mul_f32 v[64:65], v[50:51], v[64:65]
	v_add_f32_e32 v66, v66, v67
	v_pk_fma_f32 v[88:89], v[52:53], v[90:91], v[88:89] op_sel_hi:[1,0,1]
	v_pk_fma_f32 v[64:65], v[54:55], v[90:91], v[64:65] op_sel_hi:[1,0,1]
	v_add_f32_dpp v66, v66, v66 quad_perm:[1,0,3,2] row_mask:0xf bank_mask:0xf bound_ctrl:1
	v_add_f32_e32 v90, v96, v97
	v_cndmask_b32_e32 v67, v75, v90, vcc
	v_add_f32_dpp v66, v66, v66 quad_perm:[2,3,0,1] row_mask:0xf bank_mask:0xf bound_ctrl:1
	v_cndmask_b32_e32 v75, v90, v75, vcc
	ds_read_b128 v[24:27], v72 offset:25600
	ds_read_b128 v[36:39], v72 offset:25856
	v_add_f32_dpp v66, v66, v66 row_half_mirror row_mask:0xf bank_mask:0xf bound_ctrl:1
	v_add_f32_dpp v75, v67, v75 quad_perm:[1,0,3,2] row_mask:0xf bank_mask:0xf bound_ctrl:1
	ds_read_b128 v[48:51], v72 offset:27264
	ds_read_b128 v[32:35], v72 offset:26368
	v_add_f32_dpp v66, v66, v66 row_mirror row_mask:0xf bank_mask:0xf bound_ctrl:1
	v_pk_fma_f32 v[64:65], v[46:47], v[66:67], v[64:65] op_sel_hi:[1,0,1]
	v_pk_fma_f32 v[88:89], v[44:45], v[66:67], v[88:89] op_sel_hi:[1,0,1]
	s_waitcnt lgkmcnt(11)
	v_pk_mul_f32 v[66:67], v[94:95], v[64:65]
	v_pk_mul_f32 v[58:59], v[58:59], v[64:65]
	v_pk_fma_f32 v[66:67], v[92:93], v[88:89], v[66:67]
	v_pk_mul_f32 v[64:65], v[78:79], v[64:65]
	v_add_f32_e32 v66, v66, v67
	v_pk_fma_f32 v[78:79], v[56:57], v[88:89], v[58:59]
	v_pk_mul_f32 v[76:77], v[76:77], v[88:89]
	v_add_f32_dpp v66, v66, v66 quad_perm:[1,0,3,2] row_mask:0xf bank_mask:0xf bound_ctrl:1
	v_pk_fma_f32 v[64:65], v[98:99], v[82:83], v[64:65] op_sel_hi:[0,1,1]
	v_add_f32_e32 v79, v78, v79
	v_add_f32_dpp v66, v66, v66 quad_perm:[2,3,0,1] row_mask:0xf bank_mask:0xf bound_ctrl:1
	v_pk_fma_f32 v[76:77], v[98:99], v[80:81], v[76:77] op_sel_hi:[0,1,1]
	ds_read_b128 v[40:43], v72 offset:26752
	ds_read_b128 v[52:55], v72 offset:27520
	v_add_f32_dpp v66, v66, v66 row_half_mirror row_mask:0xf bank_mask:0xf bound_ctrl:1
	ds_read_b128 v[44:47], v72 offset:27008
	ds_read_b128 v[56:59], v72 offset:27776
	v_add_f32_dpp v78, v66, v66 row_mirror row_mask:0xf bank_mask:0xf bound_ctrl:1
	v_pk_fma_f32 v[64:65], v[62:63], v[78:79], v[64:65] op_sel_hi:[1,0,1]
	v_pk_fma_f32 v[66:67], v[60:61], v[78:79], v[76:77] op_sel_hi:[1,0,1]
	v_pk_mul_f32 v[60:61], v[86:87], v[64:65]
	v_pk_fma_f32 v[60:61], v[84:85], v[66:67], v[60:61]
	s_nop 0
	v_add_f32_e32 v60, v60, v61
	v_cndmask_b32_e32 v61, v79, v60, vcc
	v_cndmask_b32_e32 v60, v60, v79, vcc
	s_nop 1
	v_add_f32_dpp v60, v61, v60 quad_perm:[1,0,3,2] row_mask:0xf bank_mask:0xf bound_ctrl:1
	v_cndmask_b32_e64 v61, v75, v60, s[4:5]
	v_cndmask_b32_e64 v60, v60, v75, s[4:5]
	s_nop 1
	v_add_f32_dpp v60, v61, v60 quad_perm:[2,3,0,1] row_mask:0xf bank_mask:0xf bound_ctrl:1
	s_nop 1
	v_add_f32_dpp v60, v60, v60 row_ror:4 row_mask:0xf bank_mask:0xf bound_ctrl:1
	s_nop 1
	v_add_f32_dpp v60, v60, v60 row_ror:8 row_mask:0xf bank_mask:0xf bound_ctrl:1
	ds_write_b32 v73, v60 offset:1024
	s_waitcnt lgkmcnt(14)
; template <int CTRL> DI float dppf(float v) { return __int_as_float(__builtin_amdgcn_update_dpp(0, __float_as_int(v), CTRL, 0xf, 0xf, false)); }
; DI float red16(float p) { p += dppf<0xB1>(p); p += dppf<0x4E>(p); p += dppf<0x141>(p); p += dppf<0x140>(p); return p; }
; DI void scan_task(const Params& P, int sb, unsigned char* lds) {
;     ...
;       for (int g4 = 0; g4 < CH / 4; ++g4) {
;         const float* gb = cb + g4 * 4 * SREC;
;         const float4 v4 = *(const float4*)(vrow + g4 * 4);
;         float pp[4];
; #pragma unroll
;         for (int i = 0; i < 4; ++i) {
;           ld_ops(nx3, gb + (i + 3) * SREC, q4);
;           const f2 a01 = {cur.a.x, cur.a.y}, a23 = {cur.a.z, cur.a.w}, w01 = {cur.w.x, cur.w.y}, w23 = {cur.w.z, cur.w.w};
;           const f2 k01 = {cur.k.x, cur.k.y}, k23 = {cur.k.z, cur.k.w}, b01 = {cur.b.x, cur.b.y}, b23 = {cur.b.z, cur.b.w};
;           const f2 r01 = {cur.r.x, cur.r.y}, r23 = {cur.r.z, cur.r.w};
;           f2 pa = S0 * a01; pa += S1 * a23;
;           const float vs = (i == 0) ? v4.x : (i == 1) ? v4.y : (i == 2) ? v4.z : v4.w;
;           const f2 vv = {vs, vs};
;           const f2 t0 = S0 * w01 + vv * k01, t1 = S1 * w23 + vv * k23;
;           const float sa = red16(pa.x + pa.y);
;           const f2 sa2 = {sa, sa};
;           S0 = t0 + sa2 * b01; S1 = t1 + sa2 * b23;
;           f2 py = S0 * r01; py += S1 * r23;
;           pp[i] = py.x + py.y;
;           cur = nxt; nxt = nx2; nx2 = nx3;
;         }
;         const float tA = o1 ? pp[0] : pp[1], kA = o1 ? pp[1] : pp[0];
;         const float tB = o1 ? pp[2] : pp[3], kB = o1 ? pp[3] : pp[2];
;         const float r0 = kA + dppf<0xB1>(tA), r1 = kB + dppf<0xB1>(tB);
;         const float tC = o2 ? r0 : r1, kC = o2 ? r1 : r0;
;         float u = kC + dppf<0x4E>(tC);
;         u += dppf<0x124>(u);
;         u += dppf<0x128>(u);
;         yb[(g4 * 4 + (q & 3)) * 16 + rowl] = u;
	v_pk_mul_f32 v[2:3], v[64:65], v[2:3]
	ds_read_b128 v[60:63], v72 offset:28416
	ds_read_b128 v[76:79], v72 offset:28672
	ds_read_b128 v[80:83], v72 offset:28928
	ds_read_b128 v[84:87], v72 offset:29184
	ds_read_b128 v[88:91], v100 offset:80
	ds_read_b128 v[92:95], v72 offset:28160
	v_pk_fma_f32 v[96:97], v[66:67], v[0:1], v[2:3]
	ds_read_b128 v[0:3], v72 offset:29568
	v_add_f32_e32 v75, v96, v97
	s_waitcnt lgkmcnt(2)
	v_pk_mul_f32 v[14:15], v[14:15], v[88:89] op_sel_hi:[1,0]
	v_pk_mul_f32 v[12:13], v[12:13], v[88:89] op_sel_hi:[1,0]
	v_add_f32_dpp v75, v75, v75 quad_perm:[1,0,3,2] row_mask:0xf bank_mask:0xf bound_ctrl:1
	v_pk_fma_f32 v[64:65], v[64:65], v[10:11], v[14:15]
	v_pk_fma_f32 v[66:67], v[66:67], v[8:9], v[12:13]
	v_add_f32_dpp v75, v75, v75 quad_perm:[2,3,0,1] row_mask:0xf bank_mask:0xf bound_ctrl:1
	v_mov_b32_e32 v98, v91
	ds_read_b128 v[8:11], v72 offset:30080
	ds_read_b128 v[12:15], v72 offset:30336
	v_add_f32_dpp v75, v75, v75 row_half_mirror row_mask:0xf bank_mask:0xf bound_ctrl:1
	s_nop 1
	v_add_f32_dpp v96, v75, v75 row_mirror row_mask:0xf bank_mask:0xf bound_ctrl:1
	v_pk_fma_f32 v[64:65], v[6:7], v[96:97], v[64:65] op_sel_hi:[1,0,1]
	v_pk_fma_f32 v[66:67], v[4:5], v[96:97], v[66:67] op_sel_hi:[1,0,1]
	v_pk_mul_f32 v[18:19], v[18:19], v[64:65]
	v_pk_mul_f32 v[22:23], v[22:23], v[64:65]
	v_pk_mul_f32 v[36:37], v[36:37], v[66:67]
	v_pk_mul_f32 v[38:39], v[38:39], v[64:65]
	v_pk_fma_f32 v[64:65], v[16:17], v[66:67], v[18:19]
	v_pk_fma_f32 v[66:67], v[20:21], v[66:67], v[22:23]
	v_add_f32_e32 v75, v64, v65
	v_add_f32_e32 v64, v66, v67
	v_pk_fma_f32 v[36:37], v[28:29], v[88:89], v[36:37] op_sel:[0,1,0]
	v_pk_fma_f32 v[38:39], v[30:31], v[88:89], v[38:39] op_sel:[0,1,0]
	v_add_f32_dpp v64, v64, v64 quad_perm:[1,0,3,2] row_mask:0xf bank_mask:0xf bound_ctrl:1
	ds_read_b128 v[4:7], v72 offset:29824
	ds_read_b128 v[16:19], v72 offset:30592
	ds_read_b128 v[20:23], v72 offset:30976
	ds_read_b128 v[28:31], v72 offset:31744
	v_add_f32_dpp v64, v64, v64 quad_perm:[2,3,0,1] row_mask:0xf bank_mask:0xf bound_ctrl:1
	s_nop 1
	v_add_f32_dpp v64, v64, v64 row_half_mirror row_mask:0xf bank_mask:0xf bound_ctrl:1
	s_nop 1
	v_add_f32_dpp v64, v64, v64 row_mirror row_mask:0xf bank_mask:0xf bound_ctrl:1
	v_pk_fma_f32 v[66:67], v[24:25], v[64:65], v[36:37] op_sel_hi:[1,0,1]
	v_pk_fma_f32 v[64:65], v[26:27], v[64:65], v[38:39] op_sel_hi:[1,0,1]
	v_pk_mul_f32 v[88:89], v[48:49], v[66:67]
	v_pk_mul_f32 v[34:35], v[34:35], v[64:65]
	v_pk_mul_f32 v[42:43], v[42:43], v[64:65]
	v_pk_fma_f32 v[96:97], v[32:33], v[66:67], v[34:35]
	v_pk_fma_f32 v[66:67], v[40:41], v[66:67], v[42:43]
	v_pk_mul_f32 v[64:65], v[50:51], v[64:65]
	v_add_f32_e32 v66, v66, v67
	v_pk_fma_f32 v[88:89], v[52:53], v[90:91], v[88:89] op_sel_hi:[1,0,1]
	v_pk_fma_f32 v[64:65], v[54:55], v[90:91], v[64:65] op_sel_hi:[1,0,1]
	v_add_f32_dpp v66, v66, v66 quad_perm:[1,0,3,2] row_mask:0xf bank_mask:0xf bound_ctrl:1
	v_add_f32_e32 v90, v96, v97
	v_cndmask_b32_e32 v67, v75, v90, vcc
	v_add_f32_dpp v66, v66, v66 quad_perm:[2,3,0,1] row_mask:0xf bank_mask:0xf bound_ctrl:1
	v_cndmask_b32_e32 v75, v90, v75, vcc
	ds_read_b128 v[24:27], v72 offset:31232
	ds_read_b128 v[36:39], v72 offset:31488
	v_add_f32_dpp v66, v66, v66 row_half_mirror row_mask:0xf bank_mask:0xf bound_ctrl:1
	v_add_f32_dpp v75, v67, v75 quad_perm:[1,0,3,2] row_mask:0xf bank_mask:0xf bound_ctrl:1
	ds_read_b128 v[48:51], v72 offset:32896
	ds_read_b128 v[32:35], v72 offset:32000
	v_add_f32_dpp v66, v66, v66 row_mirror row_mask:0xf bank_mask:0xf bound_ctrl:1
	v_pk_fma_f32 v[64:65], v[46:47], v[66:67], v[64:65] op_sel_hi:[1,0,1]
	v_pk_fma_f32 v[88:89], v[44:45], v[66:67], v[88:89] op_sel_hi:[1,0,1]
	s_waitcnt lgkmcnt(11)
	v_pk_mul_f32 v[66:67], v[94:95], v[64:65]
	v_pk_mul_f32 v[58:59], v[58:59], v[64:65]
	v_pk_fma_f32 v[66:67], v[92:93], v[88:89], v[66:67]
	v_pk_mul_f32 v[64:65], v[78:79], v[64:65]
	v_add_f32_e32 v66, v66, v67
	v_pk_fma_f32 v[78:79], v[56:57], v[88:89], v[58:59]
	v_pk_mul_f32 v[76:77], v[76:77], v[88:89]
	v_add_f32_dpp v66, v66, v66 quad_perm:[1,0,3,2] row_mask:0xf bank_mask:0xf bound_ctrl:1
	v_pk_fma_f32 v[64:65], v[98:99], v[82:83], v[64:65] op_sel_hi:[0,1,1]
	v_add_f32_e32 v79, v78, v79
	v_add_f32_dpp v66, v66, v66 quad_perm:[2,3,0,1] row_mask:0xf bank_mask:0xf bound_ctrl:1
	v_pk_fma_f32 v[76:77], v[98:99], v[80:81], v[76:77] op_sel_hi:[0,1,1]
	ds_read_b128 v[40:43], v72 offset:32384
	ds_read_b128 v[52:55], v72 offset:33152
	v_add_f32_dpp v66, v66, v66 row_half_mirror row_mask:0xf bank_mask:0xf bound_ctrl:1
	ds_read_b128 v[44:47], v72 offset:32640
	ds_read_b128 v[56:59], v72 offset:33408
	v_add_f32_dpp v78, v66, v66 row_mirror row_mask:0xf bank_mask:0xf bound_ctrl:1
	v_pk_fma_f32 v[64:65], v[62:63], v[78:79], v[64:65] op_sel_hi:[1,0,1]
	v_pk_fma_f32 v[66:67], v[60:61], v[78:79], v[76:77] op_sel_hi:[1,0,1]
	v_pk_mul_f32 v[60:61], v[86:87], v[64:65]
	v_pk_fma_f32 v[60:61], v[84:85], v[66:67], v[60:61]
	s_nop 0
	v_add_f32_e32 v60, v60, v61
	v_cndmask_b32_e32 v61, v79, v60, vcc
	v_cndmask_b32_e32 v60, v60, v79, vcc
	s_nop 1
	v_add_f32_dpp v60, v61, v60 quad_perm:[1,0,3,2] row_mask:0xf bank_mask:0xf bound_ctrl:1
	v_cndmask_b32_e64 v61, v75, v60, s[4:5]
	v_cndmask_b32_e64 v60, v60, v75, s[4:5]
	s_nop 1
	v_add_f32_dpp v60, v61, v60 quad_perm:[2,3,0,1] row_mask:0xf bank_mask:0xf bound_ctrl:1
	s_nop 1
	v_add_f32_dpp v60, v60, v60 row_ror:4 row_mask:0xf bank_mask:0xf bound_ctrl:1
	s_nop 1
	v_add_f32_dpp v60, v60, v60 row_ror:8 row_mask:0xf bank_mask:0xf bound_ctrl:1
	ds_write_b32 v73, v60 offset:1280
	s_waitcnt lgkmcnt(14)
; template <int CTRL> DI float dppf(float v) { return __int_as_float(__builtin_amdgcn_update_dpp(0, __float_as_int(v), CTRL, 0xf, 0xf, false)); }
; DI float red16(float p) { p += dppf<0xB1>(p); p += dppf<0x4E>(p); p += dppf<0x141>(p); p += dppf<0x140>(p); return p; }
; DI void scan_task(const Params& P, int sb, unsigned char* lds) {
;     ...
;       for (int g4 = 0; g4 < CH / 4; ++g4) {
;         const float* gb = cb + g4 * 4 * SREC;
;         const float4 v4 = *(const float4*)(vrow + g4 * 4);
;         float pp[4];
; #pragma unroll
;         for (int i = 0; i < 4; ++i) {
;           ld_ops(nx3, gb + (i + 3) * SREC, q4);
;           const f2 a01 = {cur.a.x, cur.a.y}, a23 = {cur.a.z, cur.a.w}, w01 = {cur.w.x, cur.w.y}, w23 = {cur.w.z, cur.w.w};
;           const f2 k01 = {cur.k.x, cur.k.y}, k23 = {cur.k.z, cur.k.w}, b01 = {cur.b.x, cur.b.y}, b23 = {cur.b.z, cur.b.w};
;           const f2 r01 = {cur.r.x, cur.r.y}, r23 = {cur.r.z, cur.r.w};
;           f2 pa = S0 * a01; pa += S1 * a23;
;           const float vs = (i == 0) ? v4.x : (i == 1) ? v4.y : (i == 2) ? v4.z : v4.w;
;           const f2 vv = {vs, vs};
;           const f2 t0 = S0 * w01 + vv * k01, t1 = S1 * w23 + vv * k23;
;           const float sa = red16(pa.x + pa.y);
;           const f2 sa2 = {sa, sa};
;           S0 = t0 + sa2 * b01; S1 = t1 + sa2 * b23;
;           f2 py = S0 * r01; py += S1 * r23;
;           pp[i] = py.x + py.y;
;           cur = nxt; nxt = nx2; nx2 = nx3;
;         }
;         const float tA = o1 ? pp[0] : pp[1], kA = o1 ? pp[1] : pp[0];
;         const float tB = o1 ? pp[2] : pp[3], kB = o1 ? pp[3] : pp[2];
;         const float r0 = kA + dppf<0xB1>(tA), r1 = kB + dppf<0xB1>(tB);
;         const float tC = o2 ? r0 : r1, kC = o2 ? r1 : r0;
;         float u = kC + dppf<0x4E>(tC);
;         u += dppf<0x124>(u);
;         u += dppf<0x128>(u);
;         yb[(g4 * 4 + (q & 3)) * 16 + rowl] = u;
	v_pk_mul_f32 v[2:3], v[64:65], v[2:3]
	ds_read_b128 v[60:63], v72 offset:34048
	ds_read_b128 v[76:79], v72 offset:34304
	ds_read_b128 v[80:83], v72 offset:34560
	ds_read_b128 v[84:87], v72 offset:34816
	ds_read_b128 v[88:91], v100 offset:96
	ds_read_b128 v[92:95], v72 offset:33792
	v_pk_fma_f32 v[96:97], v[66:67], v[0:1], v[2:3]
	ds_read_b128 v[0:3], v72 offset:35200
	v_add_f32_e32 v75, v96, v97
	s_waitcnt lgkmcnt(2)
	v_pk_mul_f32 v[14:15], v[14:15], v[88:89] op_sel_hi:[1,0]
	v_pk_mul_f32 v[12:13], v[12:13], v[88:89] op_sel_hi:[1,0]
	v_add_f32_dpp v75, v75, v75 quad_perm:[1,0,3,2] row_mask:0xf bank_mask:0xf bound_ctrl:1
	v_pk_fma_f32 v[64:65], v[64:65], v[10:11], v[14:15]
	v_pk_fma_f32 v[66:67], v[66:67], v[8:9], v[12:13]
	v_add_f32_dpp v75, v75, v75 quad_perm:[2,3,0,1] row_mask:0xf bank_mask:0xf bound_ctrl:1
	v_mov_b32_e32 v98, v91
	ds_read_b128 v[8:11], v72 offset:35712
	ds_read_b128 v[12:15], v72 offset:35968
	v_add_f32_dpp v75, v75, v75 row_half_mirror row_mask:0xf bank_mask:0xf bound_ctrl:1
	s_nop 1
	v_add_f32_dpp v96, v75, v75 row_mirror row_mask:0xf bank_mask:0xf bound_ctrl:1
	v_pk_fma_f32 v[64:65], v[6:7], v[96:97], v[64:65] op_sel_hi:[1,0,1]
	v_pk_fma_f32 v[66:67], v[4:5], v[96:97], v[66:67] op_sel_hi:[1,0,1]
	v_pk_mul_f32 v[18:19], v[18:19], v[64:65]
	v_pk_mul_f32 v[22:23], v[22:23], v[64:65]
	v_pk_mul_f32 v[36:37], v[36:37], v[66:67]
	v_pk_mul_f32 v[38:39], v[38:39], v[64:65]
	v_pk_fma_f32 v[64:65], v[16:17], v[66:67], v[18:19]
	v_pk_fma_f32 v[66:67], v[20:21], v[66:67], v[22:23]
	v_add_f32_e32 v75, v64, v65
	v_add_f32_e32 v64, v66, v67
	v_pk_fma_f32 v[36:37], v[28:29], v[88:89], v[36:37] op_sel:[0,1,0]
	v_pk_fma_f32 v[38:39], v[30:31], v[88:89], v[38:39] op_sel:[0,1,0]
	v_add_f32_dpp v64, v64, v64 quad_perm:[1,0,3,2] row_mask:0xf bank_mask:0xf bound_ctrl:1
	ds_read_b128 v[4:7], v72 offset:35456
	ds_read_b128 v[16:19], v72 offset:36224
	ds_read_b128 v[20:23], v72 offset:36608
	ds_read_b128 v[28:31], v72 offset:37376
	v_add_f32_dpp v64, v64, v64 quad_perm:[2,3,0,1] row_mask:0xf bank_mask:0xf bound_ctrl:1
	s_nop 1
	v_add_f32_dpp v64, v64, v64 row_half_mirror row_mask:0xf bank_mask:0xf bound_ctrl:1
	s_nop 1
	v_add_f32_dpp v64, v64, v64 row_mirror row_mask:0xf bank_mask:0xf bound_ctrl:1
	v_pk_fma_f32 v[66:67], v[24:25], v[64:65], v[36:37] op_sel_hi:[1,0,1]
	v_pk_fma_f32 v[64:65], v[26:27], v[64:65], v[38:39] op_sel_hi:[1,0,1]
	v_pk_mul_f32 v[88:89], v[48:49], v[66:67]
	v_pk_mul_f32 v[34:35], v[34:35], v[64:65]
	v_pk_mul_f32 v[42:43], v[42:43], v[64:65]
	v_pk_fma_f32 v[96:97], v[32:33], v[66:67], v[34:35]
	v_pk_fma_f32 v[66:67], v[40:41], v[66:67], v[42:43]
	v_pk_mul_f32 v[64:65], v[50:51], v[64:65]
	v_add_f32_e32 v66, v66, v67
	v_pk_fma_f32 v[88:89], v[52:53], v[90:91], v[88:89] op_sel_hi:[1,0,1]
	v_pk_fma_f32 v[64:65], v[54:55], v[90:91], v[64:65] op_sel_hi:[1,0,1]
	v_add_f32_dpp v66, v66, v66 quad_perm:[1,0,3,2] row_mask:0xf bank_mask:0xf bound_ctrl:1
	v_add_f32_e32 v90, v96, v97
	v_cndmask_b32_e32 v67, v75, v90, vcc
	v_add_f32_dpp v66, v66, v66 quad_perm:[2,3,0,1] row_mask:0xf bank_mask:0xf bound_ctrl:1
	v_cndmask_b32_e32 v75, v90, v75, vcc
	ds_read_b128 v[24:27], v72 offset:36864
	ds_read_b128 v[36:39], v72 offset:37120
	v_add_f32_dpp v66, v66, v66 row_half_mirror row_mask:0xf bank_mask:0xf bound_ctrl:1
	v_add_f32_dpp v75, v67, v75 quad_perm:[1,0,3,2] row_mask:0xf bank_mask:0xf bound_ctrl:1
	ds_read_b128 v[48:51], v72 offset:38528
	ds_read_b128 v[32:35], v72 offset:37632
	v_add_f32_dpp v66, v66, v66 row_mirror row_mask:0xf bank_mask:0xf bound_ctrl:1
	v_pk_fma_f32 v[64:65], v[46:47], v[66:67], v[64:65] op_sel_hi:[1,0,1]
	v_pk_fma_f32 v[88:89], v[44:45], v[66:67], v[88:89] op_sel_hi:[1,0,1]
	s_waitcnt lgkmcnt(11)
	v_pk_mul_f32 v[66:67], v[94:95], v[64:65]
	v_pk_mul_f32 v[58:59], v[58:59], v[64:65]
	v_pk_fma_f32 v[66:67], v[92:93], v[88:89], v[66:67]
	v_pk_mul_f32 v[64:65], v[78:79], v[64:65]
	v_add_f32_e32 v66, v66, v67
	v_pk_fma_f32 v[78:79], v[56:57], v[88:89], v[58:59]
	v_pk_mul_f32 v[76:77], v[76:77], v[88:89]
	v_add_f32_dpp v66, v66, v66 quad_perm:[1,0,3,2] row_mask:0xf bank_mask:0xf bound_ctrl:1
	v_pk_fma_f32 v[64:65], v[98:99], v[82:83], v[64:65] op_sel_hi:[0,1,1]
	v_add_f32_e32 v79, v78, v79
	v_add_f32_dpp v66, v66, v66 quad_perm:[2,3,0,1] row_mask:0xf bank_mask:0xf bound_ctrl:1
	v_pk_fma_f32 v[76:77], v[98:99], v[80:81], v[76:77] op_sel_hi:[0,1,1]
	ds_read_b128 v[40:43], v72 offset:38016
	ds_read_b128 v[52:55], v72 offset:38784
	v_add_f32_dpp v66, v66, v66 row_half_mirror row_mask:0xf bank_mask:0xf bound_ctrl:1
	ds_read_b128 v[44:47], v72 offset:38272
	ds_read_b128 v[56:59], v72 offset:39040
	v_add_f32_dpp v78, v66, v66 row_mirror row_mask:0xf bank_mask:0xf bound_ctrl:1
	v_pk_fma_f32 v[64:65], v[62:63], v[78:79], v[64:65] op_sel_hi:[1,0,1]
	v_pk_fma_f32 v[66:67], v[60:61], v[78:79], v[76:77] op_sel_hi:[1,0,1]
	v_pk_mul_f32 v[60:61], v[86:87], v[64:65]
	v_pk_fma_f32 v[60:61], v[84:85], v[66:67], v[60:61]
	s_nop 0
	v_add_f32_e32 v60, v60, v61
	v_cndmask_b32_e32 v61, v79, v60, vcc
	v_cndmask_b32_e32 v60, v60, v79, vcc
	s_nop 1
	v_add_f32_dpp v60, v61, v60 quad_perm:[1,0,3,2] row_mask:0xf bank_mask:0xf bound_ctrl:1
	v_cndmask_b32_e64 v61, v75, v60, s[4:5]
	v_cndmask_b32_e64 v60, v60, v75, s[4:5]
	s_nop 1
	v_add_f32_dpp v60, v61, v60 quad_perm:[2,3,0,1] row_mask:0xf bank_mask:0xf bound_ctrl:1
	s_nop 1
	v_add_f32_dpp v60, v60, v60 row_ror:4 row_mask:0xf bank_mask:0xf bound_ctrl:1
	s_nop 1
	v_add_f32_dpp v60, v60, v60 row_ror:8 row_mask:0xf bank_mask:0xf bound_ctrl:1
	ds_write_b32 v73, v60 offset:1536
	s_waitcnt lgkmcnt(14)
; template <int CTRL> DI float dppf(float v) { return __int_as_float(__builtin_amdgcn_update_dpp(0, __float_as_int(v), CTRL, 0xf, 0xf, false)); }
; DI float red16(float p) { p += dppf<0xB1>(p); p += dppf<0x4E>(p); p += dppf<0x141>(p); p += dppf<0x140>(p); return p; }
; DI void scan_task(const Params& P, int sb, unsigned char* lds) {
;     ...
;     for (int c = 0; c < NCH; ++c) {
;       const float* cb = buf + (c & 1) * (CH * SREC);
;       const float* vrow = vtb + (c & 1) * (16 * CH) + rowl * CH;
;       float* yb = ybuf + (c & 1) * (CH * 16);
;       StepOps cur, nxt, nx2, nx3;
;       ld_ops(cur, cb, q4);
;       ld_ops(nxt, cb + SREC, q4);
;       ld_ops(nx2, cb + 2 * SREC, q4);
; #pragma unroll 1
;       for (int g4 = 0; g4 < CH / 4; ++g4) {
;         const float* gb = cb + g4 * 4 * SREC;
;         const float4 v4 = *(const float4*)(vrow + g4 * 4);
;         float pp[4];
; #pragma unroll
;         for (int i = 0; i < 4; ++i) {
;           ld_ops(nx3, gb + (i + 3) * SREC, q4);
;           const f2 a01 = {cur.a.x, cur.a.y}, a23 = {cur.a.z, cur.a.w}, w01 = {cur.w.x, cur.w.y}, w23 = {cur.w.z, cur.w.w};
;           const f2 k01 = {cur.k.x, cur.k.y}, k23 = {cur.k.z, cur.k.w}, b01 = {cur.b.x, cur.b.y}, b23 = {cur.b.z, cur.b.w};
;           const f2 r01 = {cur.r.x, cur.r.y}, r23 = {cur.r.z, cur.r.w};
;           f2 pa = S0 * a01; pa += S1 * a23;
;           const float vs = (i == 0) ? v4.x : (i == 1) ? v4.y : (i == 2) ? v4.z : v4.w;
;           const f2 vv = {vs, vs};
;           const f2 t0 = S0 * w01 + vv * k01, t1 = S1 * w23 + vv * k23;
;           const float sa = red16(pa.x + pa.y);
;           const f2 sa2 = {sa, sa};
;           S0 = t0 + sa2 * b01; S1 = t1 + sa2 * b23;
;           f2 py = S0 * r01; py += S1 * r23;
;           pp[i] = py.x + py.y;
;           cur = nxt; nxt = nx2; nx2 = nx3;
;         }
;         const float tA = o1 ? pp[0] : pp[1], kA = o1 ? pp[1] : pp[0];
;         const float tB = o1 ? pp[2] : pp[3], kB = o1 ? pp[3] : pp[2];
;         const float r0 = kA + dppf<0xB1>(tA), r1 = kB + dppf<0xB1>(tB);
;         const float tC = o2 ? r0 : r1, kC = o2 ? r1 : r0;
;         float u = kC + dppf<0x4E>(tC);
;         u += dppf<0x124>(u);
;         u += dppf<0x128>(u);
;         yb[(g4 * 4 + (q & 3)) * 16 + rowl] = u;
;       }
;       __syncthreads();
;     }
	v_pk_mul_f32 v[2:3], v[64:65], v[2:3]
	ds_read_b128 v[60:63], v72 offset:39680
	ds_read_b128 v[76:79], v72 offset:39936
	ds_read_b128 v[80:83], v72 offset:40192
	ds_read_b128 v[84:87], v72 offset:40448
	ds_read_b128 v[88:91], v100 offset:112
	ds_read_b128 v[92:95], v72 offset:39424
	v_pk_fma_f32 v[96:97], v[66:67], v[0:1], v[2:3]
	ds_read_b128 v[0:3], v72 offset:40832
	v_add_f32_e32 v75, v96, v97
	s_waitcnt lgkmcnt(2)
	v_pk_mul_f32 v[14:15], v[14:15], v[88:89] op_sel_hi:[1,0]
	v_pk_mul_f32 v[12:13], v[12:13], v[88:89] op_sel_hi:[1,0]
	v_add_f32_dpp v75, v75, v75 quad_perm:[1,0,3,2] row_mask:0xf bank_mask:0xf bound_ctrl:1
	v_pk_fma_f32 v[64:65], v[64:65], v[10:11], v[14:15]
	v_pk_fma_f32 v[66:67], v[66:67], v[8:9], v[12:13]
	v_add_f32_dpp v75, v75, v75 quad_perm:[2,3,0,1] row_mask:0xf bank_mask:0xf bound_ctrl:1
	v_mov_b32_e32 v98, v91
	ds_read_b128 v[8:11], v72 offset:41344
	ds_read_b128 v[12:15], v72 offset:41600
	v_add_f32_dpp v75, v75, v75 row_half_mirror row_mask:0xf bank_mask:0xf bound_ctrl:1
	s_nop 1
	v_add_f32_dpp v96, v75, v75 row_mirror row_mask:0xf bank_mask:0xf bound_ctrl:1
	v_pk_fma_f32 v[64:65], v[6:7], v[96:97], v[64:65] op_sel_hi:[1,0,1]
	v_pk_fma_f32 v[66:67], v[4:5], v[96:97], v[66:67] op_sel_hi:[1,0,1]
	v_pk_mul_f32 v[18:19], v[18:19], v[64:65]
	v_pk_mul_f32 v[22:23], v[22:23], v[64:65]
	v_pk_mul_f32 v[36:37], v[36:37], v[66:67]
	v_pk_mul_f32 v[38:39], v[38:39], v[64:65]
	v_pk_fma_f32 v[64:65], v[16:17], v[66:67], v[18:19]
	v_pk_fma_f32 v[66:67], v[20:21], v[66:67], v[22:23]
	v_add_f32_e32 v75, v64, v65
	v_add_f32_e32 v64, v66, v67
	v_pk_fma_f32 v[36:37], v[28:29], v[88:89], v[36:37] op_sel:[0,1,0]
	v_pk_fma_f32 v[38:39], v[30:31], v[88:89], v[38:39] op_sel:[0,1,0]
	v_add_f32_dpp v64, v64, v64 quad_perm:[1,0,3,2] row_mask:0xf bank_mask:0xf bound_ctrl:1
	ds_read_b128 v[4:7], v72 offset:41088
	ds_read_b128 v[16:19], v72 offset:41856
	ds_read_b128 v[20:23], v72 offset:42240
	ds_read_b128 v[28:31], v72 offset:43008
	v_add_f32_dpp v64, v64, v64 quad_perm:[2,3,0,1] row_mask:0xf bank_mask:0xf bound_ctrl:1
	s_nop 1
	v_add_f32_dpp v64, v64, v64 row_half_mirror row_mask:0xf bank_mask:0xf bound_ctrl:1
	s_nop 1
	v_add_f32_dpp v64, v64, v64 row_mirror row_mask:0xf bank_mask:0xf bound_ctrl:1
	v_pk_fma_f32 v[66:67], v[24:25], v[64:65], v[36:37] op_sel_hi:[1,0,1]
	v_pk_fma_f32 v[64:65], v[26:27], v[64:65], v[38:39] op_sel_hi:[1,0,1]
	v_pk_mul_f32 v[88:89], v[48:49], v[66:67]
	v_pk_mul_f32 v[34:35], v[34:35], v[64:65]
	v_pk_mul_f32 v[42:43], v[42:43], v[64:65]
	v_pk_fma_f32 v[96:97], v[32:33], v[66:67], v[34:35]
	v_pk_fma_f32 v[66:67], v[40:41], v[66:67], v[42:43]
	v_pk_mul_f32 v[64:65], v[50:51], v[64:65]
	v_add_f32_e32 v66, v66, v67
	v_pk_fma_f32 v[88:89], v[52:53], v[90:91], v[88:89] op_sel_hi:[1,0,1]
	v_pk_fma_f32 v[64:65], v[54:55], v[90:91], v[64:65] op_sel_hi:[1,0,1]
	v_add_f32_dpp v66, v66, v66 quad_perm:[1,0,3,2] row_mask:0xf bank_mask:0xf bound_ctrl:1
	v_add_f32_e32 v90, v96, v97
	v_cndmask_b32_e32 v67, v75, v90, vcc
	v_add_f32_dpp v66, v66, v66 quad_perm:[2,3,0,1] row_mask:0xf bank_mask:0xf bound_ctrl:1
	v_cndmask_b32_e32 v75, v90, v75, vcc
	ds_read_b128 v[24:27], v72 offset:42496
	ds_read_b128 v[36:39], v72 offset:42752
	v_add_f32_dpp v66, v66, v66 row_half_mirror row_mask:0xf bank_mask:0xf bound_ctrl:1
	v_add_f32_dpp v75, v67, v75 quad_perm:[1,0,3,2] row_mask:0xf bank_mask:0xf bound_ctrl:1
	ds_read_b128 v[48:51], v72 offset:44160
	ds_read_b128 v[32:35], v72 offset:43264
	v_add_f32_dpp v66, v66, v66 row_mirror row_mask:0xf bank_mask:0xf bound_ctrl:1
	v_pk_fma_f32 v[64:65], v[46:47], v[66:67], v[64:65] op_sel_hi:[1,0,1]
	v_pk_fma_f32 v[88:89], v[44:45], v[66:67], v[88:89] op_sel_hi:[1,0,1]
	s_waitcnt lgkmcnt(11)
	v_pk_mul_f32 v[66:67], v[94:95], v[64:65]
	v_pk_mul_f32 v[58:59], v[58:59], v[64:65]
	v_pk_fma_f32 v[66:67], v[92:93], v[88:89], v[66:67]
	v_pk_mul_f32 v[64:65], v[78:79], v[64:65]
	v_add_f32_e32 v66, v66, v67
	v_pk_fma_f32 v[78:79], v[56:57], v[88:89], v[58:59]
	v_pk_mul_f32 v[76:77], v[76:77], v[88:89]
	v_add_f32_dpp v66, v66, v66 quad_perm:[1,0,3,2] row_mask:0xf bank_mask:0xf bound_ctrl:1
	v_pk_fma_f32 v[64:65], v[98:99], v[82:83], v[64:65] op_sel_hi:[0,1,1]
	v_add_f32_e32 v79, v78, v79
	v_add_f32_dpp v66, v66, v66 quad_perm:[2,3,0,1] row_mask:0xf bank_mask:0xf bound_ctrl:1
	v_pk_fma_f32 v[76:77], v[98:99], v[80:81], v[76:77] op_sel_hi:[0,1,1]
	ds_read_b128 v[40:43], v72 offset:43648
	ds_read_b128 v[52:55], v72 offset:44416
	v_add_f32_dpp v66, v66, v66 row_half_mirror row_mask:0xf bank_mask:0xf bound_ctrl:1
	ds_read_b128 v[44:47], v72 offset:43904
	ds_read_b128 v[56:59], v72 offset:44672
	v_add_f32_dpp v78, v66, v66 row_mirror row_mask:0xf bank_mask:0xf bound_ctrl:1
	v_pk_fma_f32 v[64:65], v[62:63], v[78:79], v[64:65] op_sel_hi:[1,0,1]
	v_pk_fma_f32 v[66:67], v[60:61], v[78:79], v[76:77] op_sel_hi:[1,0,1]
	v_pk_mul_f32 v[60:61], v[86:87], v[64:65]
	v_pk_fma_f32 v[60:61], v[84:85], v[66:67], v[60:61]
	s_nop 0
	v_add_f32_e32 v60, v60, v61
	v_cndmask_b32_e32 v61, v79, v60, vcc
	v_cndmask_b32_e32 v60, v60, v79, vcc
	s_nop 1
	v_add_f32_dpp v60, v61, v60 quad_perm:[1,0,3,2] row_mask:0xf bank_mask:0xf bound_ctrl:1
	v_cndmask_b32_e64 v61, v75, v60, s[4:5]
	v_cndmask_b32_e64 v60, v60, v75, s[4:5]
	s_nop 1
	v_add_f32_dpp v60, v61, v60 quad_perm:[2,3,0,1] row_mask:0xf bank_mask:0xf bound_ctrl:1
	s_nop 1
	v_add_f32_dpp v60, v60, v60 row_ror:4 row_mask:0xf bank_mask:0xf bound_ctrl:1
	s_nop 1
	v_add_f32_dpp v60, v60, v60 row_ror:8 row_mask:0xf bank_mask:0xf bound_ctrl:1
	ds_write_b32 v73, v60 offset:1792
	s_add_i32 s0, s0, 1
	s_xor_b64 s[6:7], s[6:7], -1
	s_cmpk_eq_i32 s0, 0x108
	s_waitcnt lgkmcnt(0)
	s_barrier
	s_cbranch_scc0 .LBB0_1197
	s_mov_b64 s[4:5], 0

; #define GLOAD(kt) do { const int ko = (kt) * BK; \
;     ra0 = *(const uint4*)(gA + ko); ra1 = *(const uint4*)(gA + sA + ko); ra2 = *(const uint4*)(gA + 2 * sA + ko); ra3 = *(const uint4*)(gA + 3 * sA + ko); \
;     rb0 = *(const uint4*)(gB + ko); rb1 = *(const uint4*)(gB + sB + ko); rb2 = *(const uint4*)(gB + 2 * sB + ko); rb3 = *(const uint4*)(gB + 3 * sB + ko); } while (0)
; #define LSTORE(st) do { \
;     *(uint4*)(lA + (st) * ASZ) = ra0; *(uint4*)(lA + (st) * ASZ + 64 * LDT) = ra1; *(uint4*)(lA + (st) * ASZ + 128 * LDT) = ra2; *(uint4*)(lA + (st) * ASZ + 192 * LDT) = ra3; \
;     *(uint4*)(lB + (st) * BSZ) = rb0; *(uint4*)(lB + (st) * BSZ + 64 * LDT) = rb1; *(uint4*)(lB + (st) * BSZ + 128 * LDT) = rb2; *(uint4*)(lB + (st) * BSZ + 192 * LDT) = rb3; } while (0)
; template <class Epi>
; DI void gemm_tile(const GemmDesc g, int m0, int n0, unsigned char* lds, Epi& epi) {
;     ...
;   __syncthreads();
;   GLOAD(0);
;   LSTORE(0);
;   __syncthreads();
;   for (int kt = 0; kt < nk; kt += 2) {
;     const bool h1 = kt + 1 < nk, h2 = kt + 2 < nk;
;     if (h1) GLOAD(kt + 1);
;     COMPUTE(0);
;     if (h1) LSTORE(1);
;     __syncthreads();
;     if (h1) {
;       if (h2) GLOAD(kt + 2);
;       COMPUTE(1);
;       if (h2) LSTORE(0);
;       __syncthreads();
; DI void phase7(const Params& P, unsigned char* lds) {
;     ...
;   for (int t = blockIdx.x; t < 64 * 4; t += gridDim.x) gemm_tile(g, (t >> 2) * BM, (t & 3) * BN, lds, e);
.LBB0_1385:
	v_lshl_add_u64 v[240:241], v[168:169], 0, v[160:161]
	v_lshl_add_u64 v[238:239], v[166:167], 0, v[160:161]
	v_add_co_u32_e32 v128, vcc, 0x5a68000, v240
	s_nop 1
	v_addc_co_u32_e32 v129, vcc, 0, v241, vcc
	global_load_dwordx4 v[128:131], v[128:129], off offset:128
	v_add_co_u32_e32 v132, vcc, 0x5a88000, v240
	s_nop 1
	v_addc_co_u32_e32 v133, vcc, 0, v241, vcc
	global_load_dwordx4 v[132:135], v[132:133], off offset:128
	v_add_co_u32_e32 v136, vcc, 0x5aa8000, v240
	s_nop 1
	v_addc_co_u32_e32 v137, vcc, 0, v241, vcc
	global_load_dwordx4 v[136:139], v[136:137], off offset:128
	v_add_co_u32_e32 v140, vcc, 0x5ac8000, v240
	s_nop 1
	v_addc_co_u32_e32 v141, vcc, 0, v241, vcc
	global_load_dwordx4 v[140:143], v[140:141], off offset:128
	v_add_co_u32_e32 v144, vcc, 0x710000, v238
	s_nop 1
	v_addc_co_u32_e32 v145, vcc, 0, v239, vcc
	global_load_dwordx4 v[144:147], v[144:145], off offset:128
	v_add_co_u32_e32 v148, vcc, 0x730000, v238
	s_nop 1
	v_addc_co_u32_e32 v149, vcc, 0, v239, vcc
	global_load_dwordx4 v[148:151], v[148:149], off offset:128
	v_add_co_u32_e32 v152, vcc, 0x750000, v238
	s_nop 1
	v_addc_co_u32_e32 v153, vcc, 0, v239, vcc
	global_load_dwordx4 v[152:155], v[152:153], off offset:128
	v_add_co_u32_e32 v156, vcc, 0x770000, v238
	s_nop 1
	v_addc_co_u32_e32 v157, vcc, 0, v239, vcc
	global_load_dwordx4 v[156:159], v[156:157], off offset:128
	ds_read_b128 v[196:199], v164
	ds_read_b128 v[200:203], v163
	ds_read_b128 v[204:207], v164 offset:32
	ds_read_b128 v[210:213], v163 offset:32
	ds_read_b128 v[214:217], v163 offset:4608
	ds_read_b128 v[218:221], v163 offset:4640
	s_cmp_lt_u32 s31, 14
	s_waitcnt lgkmcnt(4)
	v_mfma_f32_32x32x16_bf16 v[112:127], v[196:199], v[200:203], v[112:127]
	s_cselect_b64 s[16:17], -1, 0
	s_cmp_gt_u32 s31, 13
	s_cselect_b64 s[14:15], -1, 0
	s_waitcnt lgkmcnt(1)
	v_mfma_f32_32x32x16_bf16 v[96:111], v[196:199], v[214:217], v[96:111]
	ds_read_b128 v[196:199], v164 offset:4608
	ds_read_b128 v[222:225], v164 offset:4640
	s_waitcnt lgkmcnt(1)
	v_mfma_f32_32x32x16_bf16 v[80:95], v[196:199], v[200:203], v[80:95]
	v_mfma_f32_32x32x16_bf16 v[64:79], v[196:199], v[214:217], v[64:79]
	ds_read_b128 v[196:199], v164 offset:9216
	ds_read_b128 v[226:229], v164 offset:9248
	s_waitcnt lgkmcnt(1)
	v_mfma_f32_32x32x16_bf16 v[48:63], v[196:199], v[200:203], v[48:63]
	v_mfma_f32_32x32x16_bf16 v[32:47], v[196:199], v[214:217], v[32:47]
	ds_read_b128 v[196:199], v164 offset:13824
	ds_read_b128 v[170:173], v164 offset:13856
	s_waitcnt lgkmcnt(1)
	v_mfma_f32_32x32x16_bf16 v[16:31], v[196:199], v[200:203], v[16:31]
	v_mfma_f32_32x32x16_bf16 v[112:127], v[204:207], v[210:213], v[112:127]
	v_mfma_f32_32x32x16_bf16 v[96:111], v[204:207], v[218:221], v[96:111]
	v_mfma_f32_32x32x16_bf16 v[0:15], v[196:199], v[214:217], v[0:15]
	ds_read_b128 v[196:199], v164 offset:64
	ds_read_b128 v[200:203], v163 offset:64
	ds_read_b128 v[204:207], v164 offset:96
	ds_read_b128 v[180:183], v163 offset:96
	v_mfma_f32_32x32x16_bf16 v[80:95], v[222:225], v[210:213], v[80:95]
	v_mfma_f32_32x32x16_bf16 v[64:79], v[222:225], v[218:221], v[64:79]
	v_mfma_f32_32x32x16_bf16 v[48:63], v[226:229], v[210:213], v[48:63]
	s_waitcnt lgkmcnt(4)
	v_mfma_f32_32x32x16_bf16 v[16:31], v[170:173], v[210:213], v[16:31]
	ds_read_b128 v[210:213], v163 offset:4672
	ds_read_b128 v[184:187], v163 offset:4704
	v_mfma_f32_32x32x16_bf16 v[32:47], v[226:229], v[218:221], v[32:47]
	s_waitcnt lgkmcnt(4)
	v_mfma_f32_32x32x16_bf16 v[112:127], v[196:199], v[200:203], v[112:127]
	s_waitcnt lgkmcnt(1)
	v_mfma_f32_32x32x16_bf16 v[96:111], v[196:199], v[210:213], v[96:111]
	ds_read_b128 v[196:199], v164 offset:4672
	ds_read_b128 v[222:225], v164 offset:4704
	v_mfma_f32_32x32x16_bf16 v[0:15], v[170:173], v[218:221], v[0:15]
	v_lshl_add_u64 v[172:173], v[168:169], 0, v[160:161]
	v_lshl_add_u64 v[170:171], v[166:167], 0, v[160:161]
	s_waitcnt lgkmcnt(1)
	v_mfma_f32_32x32x16_bf16 v[80:95], v[196:199], v[200:203], v[80:95]
	v_mfma_f32_32x32x16_bf16 v[64:79], v[196:199], v[210:213], v[64:79]
	ds_read_b128 v[196:199], v164 offset:9280
	ds_read_b128 v[188:191], v164 offset:9312
	s_waitcnt lgkmcnt(1)
	v_mfma_f32_32x32x16_bf16 v[48:63], v[196:199], v[200:203], v[48:63]
	v_mfma_f32_32x32x16_bf16 v[32:47], v[196:199], v[210:213], v[32:47]
	ds_read_b128 v[196:199], v164 offset:13888
	ds_read_b128 v[192:195], v164 offset:13920
	s_waitcnt lgkmcnt(0)
	v_mfma_f32_32x32x16_bf16 v[16:31], v[196:199], v[200:203], v[16:31]
	v_mfma_f32_32x32x16_bf16 v[0:15], v[196:199], v[210:213], v[0:15]
	s_waitcnt vmcnt(7)
	ds_write_b128 v162, v[128:131] offset:36864
	v_mfma_f32_32x32x16_bf16 v[80:95], v[222:225], v[180:183], v[80:95]
	s_waitcnt vmcnt(6)
	ds_write_b128 v162, v[132:135] offset:46080
	v_mfma_f32_32x32x16_bf16 v[64:79], v[222:225], v[184:187], v[64:79]
	s_waitcnt vmcnt(5)
	ds_write_b128 v162, v[136:139] offset:55296
	v_mfma_f32_32x32x16_bf16 v[112:127], v[204:207], v[180:183], v[112:127]
	s_waitcnt vmcnt(4)
	ds_write_b128 v162, v[140:143] offset:64512
	v_mfma_f32_32x32x16_bf16 v[96:111], v[204:207], v[184:187], v[96:111]
	s_waitcnt vmcnt(3)
	ds_write_b128 v179, v[144:147] offset:36864
	v_mfma_f32_32x32x16_bf16 v[48:63], v[188:191], v[180:183], v[48:63]
	s_waitcnt vmcnt(2)
	ds_write_b128 v179, v[148:151] offset:46080
	v_mfma_f32_32x32x16_bf16 v[32:47], v[188:191], v[184:187], v[32:47]
	s_waitcnt vmcnt(1)
	ds_write_b128 v179, v[152:155] offset:55296
	v_mfma_f32_32x32x16_bf16 v[16:31], v[192:195], v[180:183], v[16:31]
	s_waitcnt vmcnt(0)
	ds_write_b128 v179, v[156:159] offset:64512
	v_mfma_f32_32x32x16_bf16 v[0:15], v[192:195], v[184:187], v[0:15]
	s_and_b64 vcc, exec, s[14:15]
	s_waitcnt lgkmcnt(0)
	s_barrier
	s_cbranch_vccnz .LBB0_1387
	v_add_co_u32_e32 v128, vcc, 0x5a68000, v172
	s_nop 1
	v_addc_co_u32_e32 v129, vcc, 0, v173, vcc
	v_add_co_u32_e32 v132, vcc, 0x5a88000, v172
	s_nop 1
	v_addc_co_u32_e32 v133, vcc, 0, v173, vcc
	v_add_co_u32_e32 v136, vcc, 0x5aa8000, v172
	global_load_dwordx4 v[128:131], v[128:129], off offset:256
	s_nop 0
	global_load_dwordx4 v[132:135], v[132:133], off offset:256
	v_addc_co_u32_e32 v137, vcc, 0, v173, vcc
	v_add_co_u32_e32 v140, vcc, 0x5ac8000, v172
	s_nop 1
	v_addc_co_u32_e32 v141, vcc, 0, v173, vcc
	v_add_co_u32_e32 v144, vcc, 0x710000, v170
	global_load_dwordx4 v[136:139], v[136:137], off offset:256
	s_nop 0
	global_load_dwordx4 v[140:143], v[140:141], off offset:256
	v_addc_co_u32_e32 v145, vcc, 0, v171, vcc
	v_add_co_u32_e32 v148, vcc, 0x730000, v170
	s_nop 1
	v_addc_co_u32_e32 v149, vcc, 0, v171, vcc
	v_add_co_u32_e32 v152, vcc, 0x750000, v170
	global_load_dwordx4 v[144:147], v[144:145], off offset:256
	s_nop 0
	global_load_dwordx4 v[148:151], v[148:149], off offset:256
	v_addc_co_u32_e32 v153, vcc, 0, v171, vcc
	v_add_co_u32_e32 v156, vcc, 0x770000, v170
	s_nop 1
	v_addc_co_u32_e32 v157, vcc, 0, v171, vcc
	global_load_dwordx4 v[152:155], v[152:153], off offset:256
	s_nop 0
	global_load_dwordx4 v[156:159], v[156:157], off offset:256
; #define GLOAD(kt) do { const int ko = (kt) * BK; \
;     ra0 = *(const uint4*)(gA + ko); ra1 = *(const uint4*)(gA + sA + ko); ra2 = *(const uint4*)(gA + 2 * sA + ko); ra3 = *(const uint4*)(gA + 3 * sA + ko); \
;     rb0 = *(const uint4*)(gB + ko); rb1 = *(const uint4*)(gB + sB + ko); rb2 = *(const uint4*)(gB + 2 * sB + ko); rb3 = *(const uint4*)(gB + 3 * sB + ko); } while (0)
; #define LSTORE(st) do { \
;     *(uint4*)(lA + (st) * ASZ) = ra0; *(uint4*)(lA + (st) * ASZ + 64 * LDT) = ra1; *(uint4*)(lA + (st) * ASZ + 128 * LDT) = ra2; *(uint4*)(lA + (st) * ASZ + 192 * LDT) = ra3; \
;     *(uint4*)(lB + (st) * BSZ) = rb0; *(uint4*)(lB + (st) * BSZ + 64 * LDT) = rb1; *(uint4*)(lB + (st) * BSZ + 128 * LDT) = rb2; *(uint4*)(lB + (st) * BSZ + 192 * LDT) = rb3; } while (0)
; template <class Epi>
; DI void gemm_tile(const GemmDesc g, int m0, int n0, unsigned char* lds, Epi& epi) {
;     ...
;   for (int kt = 0; kt < nk; kt += 2) {
;     const bool h1 = kt + 1 < nk, h2 = kt + 2 < nk;
;     if (h1) GLOAD(kt + 1);
;     COMPUTE(0);
;     if (h1) LSTORE(1);
;     __syncthreads();
;     if (h1) {
;       if (h2) GLOAD(kt + 2);
;       COMPUTE(1);
;       if (h2) LSTORE(0);
;       __syncthreads();
;     }
; DI void xcd_barrier(const XcdBarrier& b) {
;   asm volatile("s_waitcnt vmcnt(0)" ::: "memory");
;   __syncthreads();
;   if (threadIdx.x == 0) {
;     unsigned* bar = b.bar;
;     __builtin_amdgcn_s_waitcnt(0);
;     unsigned nloc = b.st[0], nx = b.st[1];
;     if (nloc == 0u) { xcd_barrier_complete(bar, b.x, nloc, nx); b.st[0] = nloc; b.st[1] = nx; }
.LBB0_1387:
	ds_read_b128 v[170:173], v164 offset:36864
	ds_read_b128 v[180:183], v163 offset:36864
	ds_read_b128 v[184:187], v164 offset:36896
	ds_read_b128 v[188:191], v163 offset:36896
	ds_read_b128 v[192:195], v163 offset:41472
	ds_read_b128 v[196:199], v163 offset:41504
	s_andn2_b64 vcc, exec, s[16:17]
	s_waitcnt lgkmcnt(4)
	v_mfma_f32_32x32x16_bf16 v[112:127], v[170:173], v[180:183], v[112:127]
	s_waitcnt lgkmcnt(1)
	v_mfma_f32_32x32x16_bf16 v[96:111], v[170:173], v[192:195], v[96:111]
	ds_read_b128 v[170:173], v164 offset:41472
	ds_read_b128 v[200:203], v164 offset:41504
	s_waitcnt lgkmcnt(1)
	v_mfma_f32_32x32x16_bf16 v[80:95], v[170:173], v[180:183], v[80:95]
	v_mfma_f32_32x32x16_bf16 v[64:79], v[170:173], v[192:195], v[64:79]
	ds_read_b128 v[170:173], v164 offset:46080
	ds_read_b128 v[204:207], v164 offset:46112
	s_waitcnt lgkmcnt(1)
	v_mfma_f32_32x32x16_bf16 v[48:63], v[170:173], v[180:183], v[48:63]
	v_mfma_f32_32x32x16_bf16 v[32:47], v[170:173], v[192:195], v[32:47]
	ds_read_b128 v[170:173], v164 offset:50688
	ds_read_b128 v[210:213], v164 offset:50720
	s_waitcnt lgkmcnt(1)
	v_mfma_f32_32x32x16_bf16 v[16:31], v[170:173], v[180:183], v[16:31]
	v_mfma_f32_32x32x16_bf16 v[0:15], v[170:173], v[192:195], v[0:15]
	v_mfma_f32_32x32x16_bf16 v[112:127], v[184:187], v[188:191], v[112:127]
	v_mfma_f32_32x32x16_bf16 v[96:111], v[184:187], v[196:199], v[96:111]
	v_mfma_f32_32x32x16_bf16 v[80:95], v[200:203], v[188:191], v[80:95]
	v_mfma_f32_32x32x16_bf16 v[64:79], v[200:203], v[196:199], v[64:79]
	v_mfma_f32_32x32x16_bf16 v[48:63], v[204:207], v[188:191], v[48:63]
	v_mfma_f32_32x32x16_bf16 v[32:47], v[204:207], v[196:199], v[32:47]
	s_waitcnt lgkmcnt(0)
	v_mfma_f32_32x32x16_bf16 v[16:31], v[210:213], v[188:191], v[16:31]
	ds_read_b128 v[170:173], v164 offset:36928
	ds_read_b128 v[180:183], v163 offset:36928
	ds_read_b128 v[184:187], v164 offset:36960
	ds_read_b128 v[188:191], v163 offset:36960
	v_mfma_f32_32x32x16_bf16 v[0:15], v[210:213], v[196:199], v[0:15]
	ds_read_b128 v[192:195], v163 offset:41536
	ds_read_b128 v[196:199], v163 offset:41568
	s_waitcnt lgkmcnt(4)
	v_mfma_f32_32x32x16_bf16 v[112:127], v[170:173], v[180:183], v[112:127]
	s_waitcnt lgkmcnt(1)
	v_mfma_f32_32x32x16_bf16 v[96:111], v[170:173], v[192:195], v[96:111]
	ds_read_b128 v[170:173], v164 offset:41536
	ds_read_b128 v[200:203], v164 offset:41568
	s_waitcnt lgkmcnt(1)
	v_mfma_f32_32x32x16_bf16 v[80:95], v[170:173], v[180:183], v[80:95]
	v_mfma_f32_32x32x16_bf16 v[64:79], v[170:173], v[192:195], v[64:79]
	ds_read_b128 v[170:173], v164 offset:46144
	ds_read_b128 v[204:207], v164 offset:46176
	s_waitcnt lgkmcnt(1)
	v_mfma_f32_32x32x16_bf16 v[48:63], v[170:173], v[180:183], v[48:63]
	v_mfma_f32_32x32x16_bf16 v[32:47], v[170:173], v[192:195], v[32:47]
	ds_read_b128 v[170:173], v164 offset:50752
	ds_read_b128 v[210:213], v164 offset:50784
	s_waitcnt lgkmcnt(1)
	v_mfma_f32_32x32x16_bf16 v[16:31], v[170:173], v[180:183], v[16:31]
	v_mfma_f32_32x32x16_bf16 v[0:15], v[170:173], v[192:195], v[0:15]
	s_cbranch_vccnz .Lg7_b_plain
	s_waitcnt lgkmcnt(0)
	s_waitcnt vmcnt(7)
	ds_write_b128 v162, v[128:131]
	v_mfma_f32_32x32x16_bf16 v[112:127], v[184:187], v[188:191], v[112:127]
	s_waitcnt vmcnt(6)
	ds_write_b128 v162, v[132:135] offset:9216
	v_mfma_f32_32x32x16_bf16 v[96:111], v[184:187], v[196:199], v[96:111]
	s_waitcnt vmcnt(5)
	ds_write_b128 v162, v[136:139] offset:18432
	v_mfma_f32_32x32x16_bf16 v[80:95], v[200:203], v[188:191], v[80:95]
	s_waitcnt vmcnt(4)
	ds_write_b128 v162, v[140:143] offset:27648
	v_mfma_f32_32x32x16_bf16 v[64:79], v[200:203], v[196:199], v[64:79]
	s_waitcnt vmcnt(3)
	ds_write_b128 v179, v[144:147]
	v_mfma_f32_32x32x16_bf16 v[48:63], v[204:207], v[188:191], v[48:63]
	s_waitcnt vmcnt(2)
	ds_write_b128 v179, v[148:151] offset:9216
	v_mfma_f32_32x32x16_bf16 v[32:47], v[204:207], v[196:199], v[32:47]
	s_waitcnt vmcnt(1)
	ds_write_b128 v179, v[152:155] offset:18432
	v_mfma_f32_32x32x16_bf16 v[16:31], v[210:213], v[188:191], v[16:31]
	s_waitcnt vmcnt(0)
	ds_write_b128 v179, v[156:159] offset:27648
	v_mfma_f32_32x32x16_bf16 v[0:15], v[210:213], v[196:199], v[0:15]
	s_branch .LBB0_1384
.Lg7_b_plain:
	v_mfma_f32_32x32x16_bf16 v[112:127], v[184:187], v[188:191], v[112:127]
	v_mfma_f32_32x32x16_bf16 v[96:111], v[184:187], v[196:199], v[96:111]
	v_mfma_f32_32x32x16_bf16 v[80:95], v[200:203], v[188:191], v[80:95]
	v_mfma_f32_32x32x16_bf16 v[64:79], v[200:203], v[196:199], v[64:79]
	v_mfma_f32_32x32x16_bf16 v[48:63], v[204:207], v[188:191], v[48:63]
	v_mfma_f32_32x32x16_bf16 v[32:47], v[204:207], v[196:199], v[32:47]
	s_waitcnt lgkmcnt(0)
	v_mfma_f32_32x32x16_bf16 v[16:31], v[210:213], v[188:191], v[16:31]
	v_mfma_f32_32x32x16_bf16 v[0:15], v[210:213], v[196:199], v[0:15]
	s_branch .LBB0_1384
.LBB0_1389:
	s_cmp_lt_i32 s97, 9
	s_cbranch_scc1 .LBB0_1443
	s_waitcnt vmcnt(0)
	s_waitcnt vmcnt(63) expcnt(7) lgkmcnt(15)
	s_barrier
	s_and_saveexec_b64 s[4:5], s[42:43]
	s_cbranch_execz .LBB0_1442
	s_mov_b64 s[0:1], src_shared_base
	v_mov_b32_e32 v0, 0x24100
	v_mov_b32_e32 v1, s1
	s_waitcnt vmcnt(0) expcnt(0) lgkmcnt(0)
	flat_load_dword v2, v[0:1] sc0 sc1
	s_waitcnt vmcnt(0)
	v_mov_b32_e32 v0, 0x24104
	flat_load_dword v0, v[0:1] sc0 sc1
	s_waitcnt vmcnt(0) lgkmcnt(0)
	v_cmp_eq_u32_e32 vcc, 0, v2
	s_and_saveexec_b64 s[6:7], vcc
	s_cbranch_execz .LBB0_1406
	s_add_u32 s8, s94, 0xa200
	s_addc_u32 s9, s95, 0
	s_add_u32 s10, s94, 0xa400
	s_addc_u32 s11, s95, 0
	s_add_u32 s12, s94, 0xa500
	s_addc_u32 s13, s95, 0
	s_add_u32 s14, s94, 0xa600
	s_addc_u32 s15, s95, 0
	s_add_u32 s16, s94, 0xa700
	s_addc_u32 s17, s95, 0
	s_add_u32 s18, s94, 0xa800
	s_addc_u32 s19, s95, 0
	s_add_u32 s20, s94, 0xa900
	s_addc_u32 s21, s95, 0
	s_add_u32 s22, s94, 0xaa00
	s_addc_u32 s23, s95, 0
	s_add_u32 s24, s94, 0xab00
	s_addc_u32 s25, s95, 0
	s_add_u32 s26, s94, 0xac00
	s_addc_u32 s27, s95, 0
	s_add_u32 s28, s94, 0xad00
	s_addc_u32 s29, s95, 0
	s_add_u32 s30, s94, 0xae00
	s_addc_u32 s31, s95, 0
	s_add_u32 s34, s94, 0xaf00
	s_addc_u32 s35, s95, 0
	s_add_u32 s36, s94, 0xb000
	s_addc_u32 s37, s95, 0
	s_add_u32 s38, s94, 0xb100
	s_load_dword s0, s[78:79], 0xd8
	s_addc_u32 s39, s95, 0
	s_add_u32 s40, s94, 0xb200
	s_addc_u32 s41, s95, 0
	s_add_u32 s44, s94, 0xb300
	s_addc_u32 s45, s95, 0
	s_mov_b32 s1, 1
	v_mov_b32_e32 v16, 0
	s_branch .LBB0_1394
